# speedup vs baseline: 1.0347x; 1.0347x over previous
;   __device__ __forceinline__ float* ss() const { return (float*)(ws + OFF_ss); }
;   __device__ __forceinline__ bf16* z() const { return (bf16*)(ws + OFF_z); }
; __device__ __forceinline__ void gemm_phase(const GemmArgs& a, char* smem) {
;     ...
;     if (emode <= 1) {
; #pragma unroll
;       for (int ai = 0; ai < 2; ++ai)
; #pragma unroll
;         for (int m = 0; m < 4; ++m) {
;           const int row = brow + ai * 128 + wr * 64 + m * 16 + fr;
;           const float4 sq = *(const float4*)(a.ss + (long)row * 4);
;           rr[ai][m] = rsqrtf(((sq.x + sq.y) + (sq.z + sq.w)) * (1.0f / 1024.0f) + EPS);
;         }
;     }
.LBB0_214:
	v_mov_b32_e32 v192, v155
	v_readlane_b32 s2, v250, 5
	v_readlane_b32 s3, v250, 6
	v_ashrrev_i32_e32 v193, 6, v192
	v_ashrrev_i32_e32 v191, 8, v192
	v_and_b32_e32 v190, 3, v193
	v_and_b32_e32 v188, 15, v192
	v_bfe_u32 v189, v192, 4, 2
	s_mov_b64 s[6:7], -1
	s_and_b64 vcc, exec, s[2:3]
	s_cbranch_vccz .LBB0_300
	v_readlane_b32 s2, v251, 43
	v_readlane_b32 s3, v251, 44
	v_lshlrev_b32_e32 v128, 6, v191
	s_andn2_b64 vcc, exec, s[2:3]
	v_add3_u32 v158, v188, s22, v128
	v_mov_b64_e32 v[164:165], v[144:145]
	v_mov_b64_e32 v[162:163], v[146:147]
	v_mov_b64_e32 v[160:161], v[148:149]
	v_mov_b64_e32 v[156:157], v[150:151]
	s_cbranch_vccnz .LBB0_217
	v_readlane_b32 s10, v251, 57
	v_readlane_b32 s11, v251, 58
	v_ashrrev_i32_e32 v159, 31, v158
	s_mov_b32 s2, 0x3a800000
	s_mov_b32 s8, 0x45800000
	v_lshlrev_b32_e32 v128, 4, v158
	v_mov_b32_e32 v148, 0x358637bd
	s_nop 1
	global_load_dwordx4 v[132:135], v128, s[10:11] offset:256
	global_load_dwordx4 v[198:201], v128, s[10:11] offset:512
	global_load_dwordx4 v[202:205], v128, s[10:11] offset:768
	global_load_dwordx4 v[206:209], v128, s[10:11] offset:2048
	global_load_dwordx4 v[218:221], v128, s[10:11] offset:2304
	global_load_dwordx4 v[222:225], v128, s[10:11] offset:2560
	global_load_dwordx4 v[140:143], v128, s[10:11] offset:2816
	s_nop 0
	global_load_dwordx4 v[128:131], v128, s[10:11]
	s_waitcnt vmcnt(0)
	v_add_f32_e32 v144, v132, v133
	v_add_f32_e32 v145, v128, v129
	v_add_f32_e32 v146, v134, v135
	v_add_f32_e32 v147, v130, v131
	v_add_f32_e32 v144, v144, v146
	v_add_f32_e32 v145, v145, v147
	v_fma_f32 v144, v144, s2, v148
	v_fma_f32 v145, v145, s2, v148
	v_cmp_gt_f32_e32 vcc, s71, v144
	v_cmp_gt_f32_e64 s[6:7], s71, v145
	v_mul_f32_e32 v146, 0x4b800000, v144
	v_mul_f32_e32 v147, 0x4b800000, v145
	v_cndmask_b32_e32 v144, v144, v146, vcc
	v_cndmask_b32_e64 v145, v145, v147, s[6:7]
	v_rsq_f32_e32 v144, v144
	v_rsq_f32_e32 v145, v145
	s_nop 0
	v_mul_f32_e32 v146, s8, v144
	v_mul_f32_e32 v147, s8, v145
	v_cndmask_b32_e32 v156, v144, v146, vcc
	v_cndmask_b32_e64 v157, v145, v147, s[6:7]
	v_add_f32_e32 v144, v202, v203
	v_add_f32_e32 v145, v198, v199
	v_add_f32_e32 v146, v204, v205
	v_add_f32_e32 v147, v200, v201
	v_add_f32_e32 v144, v144, v146
	v_add_f32_e32 v145, v145, v147
	v_fma_f32 v144, v144, s2, v148
	v_fma_f32 v145, v145, s2, v148
	v_cmp_gt_f32_e32 vcc, s71, v144
	v_cmp_gt_f32_e64 s[6:7], s71, v145
	v_mul_f32_e32 v146, 0x4b800000, v144
	v_mul_f32_e32 v147, 0x4b800000, v145
	v_cndmask_b32_e32 v144, v144, v146, vcc
	v_cndmask_b32_e64 v145, v145, v147, s[6:7]
	v_rsq_f32_e32 v144, v144
	v_rsq_f32_e32 v145, v145
	s_nop 0
	v_mul_f32_e32 v146, s8, v144
	v_mul_f32_e32 v147, s8, v145
	v_cndmask_b32_e32 v160, v144, v146, vcc
	v_cndmask_b32_e64 v161, v145, v147, s[6:7]
	v_add_f32_e32 v144, v218, v219
	v_add_f32_e32 v145, v206, v207
	v_add_f32_e32 v146, v220, v221
	v_add_f32_e32 v147, v208, v209
	v_add_f32_e32 v144, v144, v146
	v_add_f32_e32 v145, v145, v147
	v_fma_f32 v144, v144, s2, v148
	v_fma_f32 v145, v145, s2, v148
	v_cmp_gt_f32_e32 vcc, s71, v144
	v_cmp_gt_f32_e64 s[6:7], s71, v145
	v_mul_f32_e32 v146, 0x4b800000, v144
	v_mul_f32_e32 v147, 0x4b800000, v145
	v_cndmask_b32_e32 v144, v144, v146, vcc
	v_cndmask_b32_e64 v145, v145, v147, s[6:7]
	v_rsq_f32_e32 v144, v144
	v_rsq_f32_e32 v145, v145
	s_nop 0
	v_mul_f32_e32 v146, s8, v144
	v_mul_f32_e32 v147, s8, v145
	v_cndmask_b32_e32 v162, v144, v146, vcc
	v_cndmask_b32_e64 v163, v145, v147, s[6:7]
	v_add_f32_e32 v144, v140, v141
	v_add_f32_e32 v145, v222, v223
	v_add_f32_e32 v146, v142, v143
	v_add_f32_e32 v147, v224, v225
	v_add_f32_e32 v144, v144, v146
	v_add_f32_e32 v145, v145, v147
	v_fma_f32 v144, v144, s2, v148
	v_fma_f32 v145, v145, s2, v148
	v_cmp_gt_f32_e32 vcc, s71, v144
	v_cmp_gt_f32_e64 s[6:7], s71, v145
	v_mul_f32_e32 v146, 0x4b800000, v144
	v_mul_f32_e32 v147, 0x4b800000, v145
	v_cndmask_b32_e32 v144, v144, v146, vcc
	v_cndmask_b32_e64 v145, v145, v147, s[6:7]
	v_rsq_f32_e32 v144, v144
	v_rsq_f32_e32 v145, v145
	s_nop 0
	v_mul_f32_e32 v146, s8, v144
	v_mul_f32_e32 v147, s8, v145
	v_cndmask_b32_e32 v164, v144, v146, vcc
	v_cndmask_b32_e64 v165, v145, v147, s[6:7]

; __device__ __forceinline__ float sigmoidf_(float x) { return __builtin_amdgcn_rcpf(1.0f + __expf(-x)); }
; __device__ __forceinline__ void gemm_phase(const GemmArgs& a, char* smem) {
;     ...
;     } else if (emode == 1) {
; #pragma unroll
;       for (int ai = 0; ai < 2; ++ai)
; #pragma unroll
;         for (int m = 0; m < 4; ++m) {
;           const int row = brow + ai * 128 + wr * 64 + m * 16 + fr;
;           const float r = rr[ai][m];
; #pragma unroll
;           for (int n = 0; n < 2; ++n) {
;             const int col = (bcol >> 1) + wc * 32 + n * 16 + fq * 4;
;             float h[4];
; #pragma unroll
;             for (int j = 0; j < 4; ++j) {
;               const float g = acc[ai][0][m][n][j] * r, uu = acc[ai][1][m][n][j] * r;
;               h[j] = g * sigmoidf_(g) * uu;
;             }
;             uint2 pk;
;             pk.x = pack2(h[0], h[1]);
;             pk.y = pack2(h[2], h[3]);
;             *(uint2*)(a.outb + (long)row * a.ldo + col) = pk;
;           }
;         }
.LBB0_258:
	s_and_b64 vcc, exec, s[6:7]
	s_cbranch_vccz .LBB0_260
	s_ashr_i32 s2, s56, 1
	v_lshlrev_b32_e32 v128, 5, v190
	v_and_b32_e32 v129, 1, v189
	v_lshrrev_b32_e32 v130, 1, v189
	v_lshlrev_b32_e32 v129, 4, v129
	v_lshl_add_u32 v129, v130, 3, v129
	v_add3_u32 v128, v128, s2, v129
	v_ashrrev_i32_e32 v129, 31, v128
	v_mad_i64_i32 v[132:133], s[2:3], s82, v158, 0
	v_lshl_add_u64 v[132:133], v[132:133], 1, s[60:61]
	v_lshl_add_u64 v[132:133], v[128:129], 1, v[132:133]
	s_lshl_b32 s8, s82, 5
	s_mov_b32 s9, 0
	v_pk_mul_f32 v[130:131], v[116:117], v[156:157] op_sel:[0,1]
	v_pk_mul_f32 v[138:139], v[118:119], v[156:157] op_sel:[0,1]
	v_pk_mul_f32 v[134:135], v[124:125], v[156:157] op_sel:[0,1]
	v_pk_mul_f32 v[140:141], v[126:127], v[156:157] op_sel:[0,1]
	v_mul_f32_e32 v136, 0xbfb8aa3b, v130
	v_mul_f32_e32 v137, 0xbfb8aa3b, v131
	v_mul_f32_e32 v142, 0xbfb8aa3b, v138
	v_mul_f32_e32 v143, 0xbfb8aa3b, v139
	v_exp_f32_e32 v136, v136
	v_exp_f32_e32 v137, v137
	v_exp_f32_e32 v142, v142
	v_exp_f32_e32 v143, v143
	v_add_f32_e32 v136, 1.0, v136
	v_add_f32_e32 v137, 1.0, v137
	v_add_f32_e32 v142, 1.0, v142
	v_add_f32_e32 v143, 1.0, v143
	v_rcp_f32_e32 v136, v136
	v_rcp_f32_e32 v137, v137
	v_rcp_f32_e32 v142, v142
	v_rcp_f32_e32 v143, v143
	s_nop 0
	v_pk_mul_f32 v[130:131], v[130:131], v[136:137]
	v_pk_mul_f32 v[138:139], v[138:139], v[142:143]
	v_pk_mul_f32 v[130:131], v[134:135], v[130:131]
	v_pk_mul_f32 v[138:139], v[140:141], v[138:139]
	v_cvt_pk_bf16_f32 v144, v130, v131
	v_cvt_pk_bf16_f32 v145, v138, v139
	v_pk_mul_f32 v[130:131], v[112:113], v[156:157] op_sel:[0,1]
	v_pk_mul_f32 v[138:139], v[114:115], v[156:157] op_sel:[0,1]
	v_pk_mul_f32 v[134:135], v[120:121], v[156:157] op_sel:[0,1]
	v_pk_mul_f32 v[140:141], v[122:123], v[156:157] op_sel:[0,1]
	v_mul_f32_e32 v136, 0xbfb8aa3b, v130
	v_mul_f32_e32 v137, 0xbfb8aa3b, v131
	v_mul_f32_e32 v142, 0xbfb8aa3b, v138
	v_mul_f32_e32 v143, 0xbfb8aa3b, v139
	v_exp_f32_e32 v136, v136
	v_exp_f32_e32 v137, v137
	v_exp_f32_e32 v142, v142
	v_exp_f32_e32 v143, v143
	v_add_f32_e32 v136, 1.0, v136
	v_add_f32_e32 v137, 1.0, v137
	v_add_f32_e32 v142, 1.0, v142
	v_add_f32_e32 v143, 1.0, v143
	v_rcp_f32_e32 v136, v136
	v_rcp_f32_e32 v137, v137
	v_rcp_f32_e32 v142, v142
	v_rcp_f32_e32 v143, v143
	s_nop 0
	v_pk_mul_f32 v[130:131], v[130:131], v[136:137]
	v_pk_mul_f32 v[138:139], v[138:139], v[142:143]
	v_pk_mul_f32 v[130:131], v[134:135], v[130:131]
	v_pk_mul_f32 v[138:139], v[140:141], v[138:139]
	v_cvt_pk_bf16_f32 v146, v130, v131
	v_cvt_pk_bf16_f32 v147, v138, v139
	s_nop 1
	v_permlane16_swap_b32_e32 v144, v146
	v_permlane16_swap_b32_e32 v145, v147
	global_store_dwordx4 v[132:133], v[144:147], off
	v_lshl_add_u64 v[132:133], v[132:133], 0, s[8:9]
	v_pk_mul_f32 v[130:131], v[96:97], v[156:157] op_sel_hi:[1,0]
	v_pk_mul_f32 v[138:139], v[98:99], v[156:157] op_sel_hi:[1,0]
	v_pk_mul_f32 v[134:135], v[104:105], v[156:157] op_sel_hi:[1,0]
	v_pk_mul_f32 v[140:141], v[106:107], v[156:157] op_sel_hi:[1,0]
	v_mul_f32_e32 v136, 0xbfb8aa3b, v130
	v_mul_f32_e32 v137, 0xbfb8aa3b, v131
	v_mul_f32_e32 v142, 0xbfb8aa3b, v138
	v_mul_f32_e32 v143, 0xbfb8aa3b, v139
	v_exp_f32_e32 v136, v136
	v_exp_f32_e32 v137, v137
	v_exp_f32_e32 v142, v142
	v_exp_f32_e32 v143, v143
	v_add_f32_e32 v136, 1.0, v136
	v_add_f32_e32 v137, 1.0, v137
	v_add_f32_e32 v142, 1.0, v142
	v_add_f32_e32 v143, 1.0, v143
	v_rcp_f32_e32 v136, v136
	v_rcp_f32_e32 v137, v137
	v_rcp_f32_e32 v142, v142
	v_rcp_f32_e32 v143, v143
	s_nop 0
	v_pk_mul_f32 v[130:131], v[130:131], v[136:137]
	v_pk_mul_f32 v[138:139], v[138:139], v[142:143]
	v_pk_mul_f32 v[130:131], v[134:135], v[130:131]
	v_pk_mul_f32 v[138:139], v[140:141], v[138:139]
	v_cvt_pk_bf16_f32 v148, v130, v131
	v_cvt_pk_bf16_f32 v149, v138, v139
	v_pk_mul_f32 v[130:131], v[100:101], v[156:157] op_sel_hi:[1,0]
	v_pk_mul_f32 v[138:139], v[102:103], v[156:157] op_sel_hi:[1,0]
	v_pk_mul_f32 v[134:135], v[108:109], v[156:157] op_sel_hi:[1,0]
	v_pk_mul_f32 v[140:141], v[110:111], v[156:157] op_sel_hi:[1,0]
	v_mul_f32_e32 v136, 0xbfb8aa3b, v130
	v_mul_f32_e32 v137, 0xbfb8aa3b, v131
	v_mul_f32_e32 v142, 0xbfb8aa3b, v138
	v_mul_f32_e32 v143, 0xbfb8aa3b, v139
	v_exp_f32_e32 v136, v136
	v_exp_f32_e32 v137, v137
	v_exp_f32_e32 v142, v142
	v_exp_f32_e32 v143, v143
	v_add_f32_e32 v136, 1.0, v136
	v_add_f32_e32 v137, 1.0, v137
	v_add_f32_e32 v142, 1.0, v142
	v_add_f32_e32 v143, 1.0, v143
	v_rcp_f32_e32 v136, v136
	v_rcp_f32_e32 v137, v137
	v_rcp_f32_e32 v142, v142
	v_rcp_f32_e32 v143, v143
	s_nop 0
	v_pk_mul_f32 v[130:131], v[130:131], v[136:137]
	v_pk_mul_f32 v[138:139], v[138:139], v[142:143]
	v_pk_mul_f32 v[130:131], v[134:135], v[130:131]
	v_pk_mul_f32 v[138:139], v[140:141], v[138:139]
	v_cvt_pk_bf16_f32 v150, v130, v131
	v_cvt_pk_bf16_f32 v151, v138, v139
	s_nop 1
	v_permlane16_swap_b32_e32 v148, v150
	v_permlane16_swap_b32_e32 v149, v151
	global_store_dwordx4 v[132:133], v[148:151], off
	v_lshl_add_u64 v[132:133], v[132:133], 0, s[8:9]
	v_pk_mul_f32 v[130:131], v[80:81], v[160:161] op_sel:[0,1]
	v_pk_mul_f32 v[138:139], v[82:83], v[160:161] op_sel:[0,1]
	v_pk_mul_f32 v[134:135], v[88:89], v[160:161] op_sel:[0,1]
	v_pk_mul_f32 v[140:141], v[90:91], v[160:161] op_sel:[0,1]
	v_mul_f32_e32 v136, 0xbfb8aa3b, v130
	v_mul_f32_e32 v137, 0xbfb8aa3b, v131
	v_mul_f32_e32 v142, 0xbfb8aa3b, v138
	v_mul_f32_e32 v143, 0xbfb8aa3b, v139
	v_exp_f32_e32 v136, v136
	v_exp_f32_e32 v137, v137
	v_exp_f32_e32 v142, v142
	v_exp_f32_e32 v143, v143
	v_add_f32_e32 v136, 1.0, v136
	v_add_f32_e32 v137, 1.0, v137
	v_add_f32_e32 v142, 1.0, v142
	v_add_f32_e32 v143, 1.0, v143
	v_rcp_f32_e32 v136, v136
	v_rcp_f32_e32 v137, v137
	v_rcp_f32_e32 v142, v142
; __device__ __forceinline__ float sigmoidf_(float x) { return __builtin_amdgcn_rcpf(1.0f + __expf(-x)); }
; __device__ __forceinline__ void gemm_phase(const GemmArgs& a, char* smem) {
;     ...
;     } else if (emode == 1) {
; #pragma unroll
;       for (int ai = 0; ai < 2; ++ai)
; #pragma unroll
;         for (int m = 0; m < 4; ++m) {
;           const int row = brow + ai * 128 + wr * 64 + m * 16 + fr;
;           const float r = rr[ai][m];
; #pragma unroll
;           for (int n = 0; n < 2; ++n) {
;             const int col = (bcol >> 1) + wc * 32 + n * 16 + fq * 4;
;             float h[4];
; #pragma unroll
;             for (int j = 0; j < 4; ++j) {
;               const float g = acc[ai][0][m][n][j] * r, uu = acc[ai][1][m][n][j] * r;
;               h[j] = g * sigmoidf_(g) * uu;
;             }
;             uint2 pk;
;             pk.x = pack2(h[0], h[1]);
;             pk.y = pack2(h[2], h[3]);
;             *(uint2*)(a.outb + (long)row * a.ldo + col) = pk;
;           }
;         }
	v_rcp_f32_e32 v143, v143
	s_nop 0
	v_pk_mul_f32 v[130:131], v[130:131], v[136:137]
	v_pk_mul_f32 v[138:139], v[138:139], v[142:143]
	v_pk_mul_f32 v[130:131], v[134:135], v[130:131]
	v_pk_mul_f32 v[138:139], v[140:141], v[138:139]
	v_cvt_pk_bf16_f32 v144, v130, v131
	v_cvt_pk_bf16_f32 v145, v138, v139
	v_pk_mul_f32 v[130:131], v[84:85], v[160:161] op_sel:[0,1]
	v_pk_mul_f32 v[138:139], v[86:87], v[160:161] op_sel:[0,1]
	v_pk_mul_f32 v[134:135], v[92:93], v[160:161] op_sel:[0,1]
	v_pk_mul_f32 v[140:141], v[94:95], v[160:161] op_sel:[0,1]
	v_mul_f32_e32 v136, 0xbfb8aa3b, v130
	v_mul_f32_e32 v137, 0xbfb8aa3b, v131
	v_mul_f32_e32 v142, 0xbfb8aa3b, v138
	v_mul_f32_e32 v143, 0xbfb8aa3b, v139
	v_exp_f32_e32 v136, v136
	v_exp_f32_e32 v137, v137
	v_exp_f32_e32 v142, v142
	v_exp_f32_e32 v143, v143
	v_add_f32_e32 v136, 1.0, v136
	v_add_f32_e32 v137, 1.0, v137
	v_add_f32_e32 v142, 1.0, v142
	v_add_f32_e32 v143, 1.0, v143
	v_rcp_f32_e32 v136, v136
	v_rcp_f32_e32 v137, v137
	v_rcp_f32_e32 v142, v142
	v_rcp_f32_e32 v143, v143
	s_nop 0
	v_pk_mul_f32 v[130:131], v[130:131], v[136:137]
	v_pk_mul_f32 v[138:139], v[138:139], v[142:143]
	v_pk_mul_f32 v[130:131], v[134:135], v[130:131]
	v_pk_mul_f32 v[138:139], v[140:141], v[138:139]
	v_cvt_pk_bf16_f32 v146, v130, v131
	v_cvt_pk_bf16_f32 v147, v138, v139
	s_nop 1
	v_permlane16_swap_b32_e32 v144, v146
	v_permlane16_swap_b32_e32 v145, v147
	global_store_dwordx4 v[132:133], v[144:147], off
	v_lshl_add_u64 v[132:133], v[132:133], 0, s[8:9]
	v_pk_mul_f32 v[130:131], v[64:65], v[160:161] op_sel_hi:[1,0]
	v_pk_mul_f32 v[138:139], v[66:67], v[160:161] op_sel_hi:[1,0]
	v_pk_mul_f32 v[134:135], v[72:73], v[160:161] op_sel_hi:[1,0]
	v_pk_mul_f32 v[140:141], v[74:75], v[160:161] op_sel_hi:[1,0]
	v_mul_f32_e32 v136, 0xbfb8aa3b, v130
	v_mul_f32_e32 v137, 0xbfb8aa3b, v131
	v_mul_f32_e32 v142, 0xbfb8aa3b, v138
	v_mul_f32_e32 v143, 0xbfb8aa3b, v139
	v_exp_f32_e32 v136, v136
	v_exp_f32_e32 v137, v137
	v_exp_f32_e32 v142, v142
	v_exp_f32_e32 v143, v143
	v_add_f32_e32 v136, 1.0, v136
	v_add_f32_e32 v137, 1.0, v137
	v_add_f32_e32 v142, 1.0, v142
	v_add_f32_e32 v143, 1.0, v143
	v_rcp_f32_e32 v136, v136
	v_rcp_f32_e32 v137, v137
	v_rcp_f32_e32 v142, v142
	v_rcp_f32_e32 v143, v143
	s_nop 0
	v_pk_mul_f32 v[130:131], v[130:131], v[136:137]
	v_pk_mul_f32 v[138:139], v[138:139], v[142:143]
	v_pk_mul_f32 v[130:131], v[134:135], v[130:131]
	v_pk_mul_f32 v[138:139], v[140:141], v[138:139]
	v_cvt_pk_bf16_f32 v148, v130, v131
	v_cvt_pk_bf16_f32 v149, v138, v139
	v_pk_mul_f32 v[130:131], v[68:69], v[160:161] op_sel_hi:[1,0]
	v_pk_mul_f32 v[138:139], v[70:71], v[160:161] op_sel_hi:[1,0]
	v_pk_mul_f32 v[134:135], v[76:77], v[160:161] op_sel_hi:[1,0]
	v_pk_mul_f32 v[140:141], v[78:79], v[160:161] op_sel_hi:[1,0]
	v_mul_f32_e32 v136, 0xbfb8aa3b, v130
	v_mul_f32_e32 v137, 0xbfb8aa3b, v131
	v_mul_f32_e32 v142, 0xbfb8aa3b, v138
	v_mul_f32_e32 v143, 0xbfb8aa3b, v139
	v_exp_f32_e32 v136, v136
	v_exp_f32_e32 v137, v137
	v_exp_f32_e32 v142, v142
	v_exp_f32_e32 v143, v143
	v_add_f32_e32 v136, 1.0, v136
	v_add_f32_e32 v137, 1.0, v137
	v_add_f32_e32 v142, 1.0, v142
	v_add_f32_e32 v143, 1.0, v143
	v_rcp_f32_e32 v136, v136
	v_rcp_f32_e32 v137, v137
	v_rcp_f32_e32 v142, v142
	v_rcp_f32_e32 v143, v143
	s_nop 0
	v_pk_mul_f32 v[130:131], v[130:131], v[136:137]
	v_pk_mul_f32 v[138:139], v[138:139], v[142:143]
	v_pk_mul_f32 v[130:131], v[134:135], v[130:131]
	v_pk_mul_f32 v[138:139], v[140:141], v[138:139]
	v_cvt_pk_bf16_f32 v150, v130, v131
	v_cvt_pk_bf16_f32 v151, v138, v139
	s_nop 1
	v_permlane16_swap_b32_e32 v148, v150
	v_permlane16_swap_b32_e32 v149, v151
	global_store_dwordx4 v[132:133], v[148:151], off
	v_lshl_add_u64 v[132:133], v[132:133], 0, s[8:9]
	v_lshl_add_u64 v[132:133], v[132:133], 0, s[8:9]
	v_lshl_add_u64 v[132:133], v[132:133], 0, s[8:9]
	v_lshl_add_u64 v[132:133], v[132:133], 0, s[8:9]
	v_lshl_add_u64 v[132:133], v[132:133], 0, s[8:9]
	v_pk_mul_f32 v[130:131], v[48:49], v[162:163] op_sel:[0,1]
	v_pk_mul_f32 v[138:139], v[50:51], v[162:163] op_sel:[0,1]
	v_pk_mul_f32 v[134:135], v[56:57], v[162:163] op_sel:[0,1]
	v_pk_mul_f32 v[140:141], v[58:59], v[162:163] op_sel:[0,1]
	v_mul_f32_e32 v136, 0xbfb8aa3b, v130
	v_mul_f32_e32 v137, 0xbfb8aa3b, v131
	v_mul_f32_e32 v142, 0xbfb8aa3b, v138
	v_mul_f32_e32 v143, 0xbfb8aa3b, v139
	v_exp_f32_e32 v136, v136
	v_exp_f32_e32 v137, v137
	v_exp_f32_e32 v142, v142
	v_exp_f32_e32 v143, v143
	v_add_f32_e32 v136, 1.0, v136
	v_add_f32_e32 v137, 1.0, v137
	v_add_f32_e32 v142, 1.0, v142
	v_add_f32_e32 v143, 1.0, v143
	v_rcp_f32_e32 v136, v136
	v_rcp_f32_e32 v137, v137
	v_rcp_f32_e32 v142, v142
	v_rcp_f32_e32 v143, v143
	s_nop 0
	v_pk_mul_f32 v[130:131], v[130:131], v[136:137]
	v_pk_mul_f32 v[138:139], v[138:139], v[142:143]
	v_pk_mul_f32 v[130:131], v[134:135], v[130:131]
	v_pk_mul_f32 v[138:139], v[140:141], v[138:139]
	v_cvt_pk_bf16_f32 v144, v130, v131
	v_cvt_pk_bf16_f32 v145, v138, v139
	v_pk_mul_f32 v[130:131], v[52:53], v[162:163] op_sel:[0,1]
	v_pk_mul_f32 v[138:139], v[54:55], v[162:163] op_sel:[0,1]
	v_pk_mul_f32 v[134:135], v[60:61], v[162:163] op_sel:[0,1]
	v_pk_mul_f32 v[140:141], v[62:63], v[162:163] op_sel:[0,1]
	v_mul_f32_e32 v136, 0xbfb8aa3b, v130
	v_mul_f32_e32 v137, 0xbfb8aa3b, v131
	v_mul_f32_e32 v142, 0xbfb8aa3b, v138
	v_mul_f32_e32 v143, 0xbfb8aa3b, v139
	v_exp_f32_e32 v136, v136
	v_exp_f32_e32 v137, v137
	v_exp_f32_e32 v142, v142
	v_exp_f32_e32 v143, v143
	v_add_f32_e32 v136, 1.0, v136
	v_add_f32_e32 v137, 1.0, v137
	v_add_f32_e32 v142, 1.0, v142
	v_add_f32_e32 v143, 1.0, v143
	v_rcp_f32_e32 v136, v136
	v_rcp_f32_e32 v137, v137
	v_rcp_f32_e32 v142, v142
	v_rcp_f32_e32 v143, v143
	s_nop 0
; __device__ __forceinline__ float sigmoidf_(float x) { return __builtin_amdgcn_rcpf(1.0f + __expf(-x)); }
; __device__ __forceinline__ void gemm_phase(const GemmArgs& a, char* smem) {
;     ...
;     } else if (emode == 1) {
; #pragma unroll
;       for (int ai = 0; ai < 2; ++ai)
; #pragma unroll
;         for (int m = 0; m < 4; ++m) {
;           const int row = brow + ai * 128 + wr * 64 + m * 16 + fr;
;           const float r = rr[ai][m];
; #pragma unroll
;           for (int n = 0; n < 2; ++n) {
;             const int col = (bcol >> 1) + wc * 32 + n * 16 + fq * 4;
;             float h[4];
; #pragma unroll
;             for (int j = 0; j < 4; ++j) {
;               const float g = acc[ai][0][m][n][j] * r, uu = acc[ai][1][m][n][j] * r;
;               h[j] = g * sigmoidf_(g) * uu;
;             }
;             uint2 pk;
;             pk.x = pack2(h[0], h[1]);
;             pk.y = pack2(h[2], h[3]);
;             *(uint2*)(a.outb + (long)row * a.ldo + col) = pk;
;           }
;         }
	v_pk_mul_f32 v[130:131], v[130:131], v[136:137]
	v_pk_mul_f32 v[138:139], v[138:139], v[142:143]
	v_pk_mul_f32 v[130:131], v[134:135], v[130:131]
	v_pk_mul_f32 v[138:139], v[140:141], v[138:139]
	v_cvt_pk_bf16_f32 v146, v130, v131
	v_cvt_pk_bf16_f32 v147, v138, v139
	s_nop 1
	v_permlane16_swap_b32_e32 v144, v146
	v_permlane16_swap_b32_e32 v145, v147
	global_store_dwordx4 v[132:133], v[144:147], off
	v_lshl_add_u64 v[132:133], v[132:133], 0, s[8:9]
	v_pk_mul_f32 v[130:131], v[32:33], v[162:163] op_sel_hi:[1,0]
	v_pk_mul_f32 v[138:139], v[34:35], v[162:163] op_sel_hi:[1,0]
	v_pk_mul_f32 v[134:135], v[40:41], v[162:163] op_sel_hi:[1,0]
	v_pk_mul_f32 v[140:141], v[42:43], v[162:163] op_sel_hi:[1,0]
	v_mul_f32_e32 v136, 0xbfb8aa3b, v130
	v_mul_f32_e32 v137, 0xbfb8aa3b, v131
	v_mul_f32_e32 v142, 0xbfb8aa3b, v138
	v_mul_f32_e32 v143, 0xbfb8aa3b, v139
	v_exp_f32_e32 v136, v136
	v_exp_f32_e32 v137, v137
	v_exp_f32_e32 v142, v142
	v_exp_f32_e32 v143, v143
	v_add_f32_e32 v136, 1.0, v136
	v_add_f32_e32 v137, 1.0, v137
	v_add_f32_e32 v142, 1.0, v142
	v_add_f32_e32 v143, 1.0, v143
	v_rcp_f32_e32 v136, v136
	v_rcp_f32_e32 v137, v137
	v_rcp_f32_e32 v142, v142
	v_rcp_f32_e32 v143, v143
	s_nop 0
	v_pk_mul_f32 v[130:131], v[130:131], v[136:137]
	v_pk_mul_f32 v[138:139], v[138:139], v[142:143]
	v_pk_mul_f32 v[130:131], v[134:135], v[130:131]
	v_pk_mul_f32 v[138:139], v[140:141], v[138:139]
	v_cvt_pk_bf16_f32 v148, v130, v131
	v_cvt_pk_bf16_f32 v149, v138, v139
	v_pk_mul_f32 v[130:131], v[36:37], v[162:163] op_sel_hi:[1,0]
	v_pk_mul_f32 v[138:139], v[38:39], v[162:163] op_sel_hi:[1,0]
	v_pk_mul_f32 v[134:135], v[44:45], v[162:163] op_sel_hi:[1,0]
	v_pk_mul_f32 v[140:141], v[46:47], v[162:163] op_sel_hi:[1,0]
	v_mul_f32_e32 v136, 0xbfb8aa3b, v130
	v_mul_f32_e32 v137, 0xbfb8aa3b, v131
	v_mul_f32_e32 v142, 0xbfb8aa3b, v138
	v_mul_f32_e32 v143, 0xbfb8aa3b, v139
	v_exp_f32_e32 v136, v136
	v_exp_f32_e32 v137, v137
	v_exp_f32_e32 v142, v142
	v_exp_f32_e32 v143, v143
	v_add_f32_e32 v136, 1.0, v136
	v_add_f32_e32 v137, 1.0, v137
	v_add_f32_e32 v142, 1.0, v142
	v_add_f32_e32 v143, 1.0, v143
	v_rcp_f32_e32 v136, v136
	v_rcp_f32_e32 v137, v137
	v_rcp_f32_e32 v142, v142
	v_rcp_f32_e32 v143, v143
	s_nop 0
	v_pk_mul_f32 v[130:131], v[130:131], v[136:137]
	v_pk_mul_f32 v[138:139], v[138:139], v[142:143]
	v_pk_mul_f32 v[130:131], v[134:135], v[130:131]
	v_pk_mul_f32 v[138:139], v[140:141], v[138:139]
	v_cvt_pk_bf16_f32 v150, v130, v131
	v_cvt_pk_bf16_f32 v151, v138, v139
	s_nop 1
	v_permlane16_swap_b32_e32 v148, v150
	v_permlane16_swap_b32_e32 v149, v151
	global_store_dwordx4 v[132:133], v[148:151], off
	v_lshl_add_u64 v[132:133], v[132:133], 0, s[8:9]
	v_pk_mul_f32 v[130:131], v[16:17], v[164:165] op_sel:[0,1]
	v_pk_mul_f32 v[138:139], v[18:19], v[164:165] op_sel:[0,1]
	v_pk_mul_f32 v[134:135], v[24:25], v[164:165] op_sel:[0,1]
	v_pk_mul_f32 v[140:141], v[26:27], v[164:165] op_sel:[0,1]
	v_mul_f32_e32 v136, 0xbfb8aa3b, v130
	v_mul_f32_e32 v137, 0xbfb8aa3b, v131
	v_mul_f32_e32 v142, 0xbfb8aa3b, v138
	v_mul_f32_e32 v143, 0xbfb8aa3b, v139
	v_exp_f32_e32 v136, v136
	v_exp_f32_e32 v137, v137
	v_exp_f32_e32 v142, v142
	v_exp_f32_e32 v143, v143
	v_add_f32_e32 v136, 1.0, v136
	v_add_f32_e32 v137, 1.0, v137
	v_add_f32_e32 v142, 1.0, v142
	v_add_f32_e32 v143, 1.0, v143
	v_rcp_f32_e32 v136, v136
	v_rcp_f32_e32 v137, v137
	v_rcp_f32_e32 v142, v142
	v_rcp_f32_e32 v143, v143
	s_nop 0
	v_pk_mul_f32 v[130:131], v[130:131], v[136:137]
	v_pk_mul_f32 v[138:139], v[138:139], v[142:143]
	v_pk_mul_f32 v[130:131], v[134:135], v[130:131]
	v_pk_mul_f32 v[138:139], v[140:141], v[138:139]
	v_cvt_pk_bf16_f32 v144, v130, v131
	v_cvt_pk_bf16_f32 v145, v138, v139
	v_pk_mul_f32 v[130:131], v[20:21], v[164:165] op_sel:[0,1]
	v_pk_mul_f32 v[138:139], v[22:23], v[164:165] op_sel:[0,1]
	v_pk_mul_f32 v[134:135], v[28:29], v[164:165] op_sel:[0,1]
	v_pk_mul_f32 v[140:141], v[30:31], v[164:165] op_sel:[0,1]
	v_mul_f32_e32 v136, 0xbfb8aa3b, v130
	v_mul_f32_e32 v137, 0xbfb8aa3b, v131
	v_mul_f32_e32 v142, 0xbfb8aa3b, v138
	v_mul_f32_e32 v143, 0xbfb8aa3b, v139
	v_exp_f32_e32 v136, v136
	v_exp_f32_e32 v137, v137
	v_exp_f32_e32 v142, v142
	v_exp_f32_e32 v143, v143
	v_add_f32_e32 v136, 1.0, v136
	v_add_f32_e32 v137, 1.0, v137
	v_add_f32_e32 v142, 1.0, v142
	v_add_f32_e32 v143, 1.0, v143
	v_rcp_f32_e32 v136, v136
	v_rcp_f32_e32 v137, v137
	v_rcp_f32_e32 v142, v142
	v_rcp_f32_e32 v143, v143
	s_nop 0
	v_pk_mul_f32 v[130:131], v[130:131], v[136:137]
	v_pk_mul_f32 v[138:139], v[138:139], v[142:143]
	v_pk_mul_f32 v[130:131], v[134:135], v[130:131]
	v_pk_mul_f32 v[138:139], v[140:141], v[138:139]
	v_cvt_pk_bf16_f32 v146, v130, v131
	v_cvt_pk_bf16_f32 v147, v138, v139
	s_nop 1
	v_permlane16_swap_b32_e32 v144, v146
	v_permlane16_swap_b32_e32 v145, v147
	global_store_dwordx4 v[132:133], v[144:147], off
	v_lshl_add_u64 v[132:133], v[132:133], 0, s[8:9]
	v_pk_mul_f32 v[130:131], v[0:1], v[164:165] op_sel_hi:[1,0]
	v_pk_mul_f32 v[138:139], v[2:3], v[164:165] op_sel_hi:[1,0]
	v_pk_mul_f32 v[134:135], v[8:9], v[164:165] op_sel_hi:[1,0]
	v_pk_mul_f32 v[140:141], v[10:11], v[164:165] op_sel_hi:[1,0]
	v_mul_f32_e32 v136, 0xbfb8aa3b, v130
	v_mul_f32_e32 v137, 0xbfb8aa3b, v131
	v_mul_f32_e32 v142, 0xbfb8aa3b, v138
	v_mul_f32_e32 v143, 0xbfb8aa3b, v139
	v_exp_f32_e32 v136, v136
	v_exp_f32_e32 v137, v137
	v_exp_f32_e32 v142, v142
	v_exp_f32_e32 v143, v143
	v_add_f32_e32 v136, 1.0, v136
	v_add_f32_e32 v137, 1.0, v137
	v_add_f32_e32 v142, 1.0, v142
	v_add_f32_e32 v143, 1.0, v143
	v_rcp_f32_e32 v136, v136
	v_rcp_f32_e32 v137, v137
	v_rcp_f32_e32 v142, v142
	v_rcp_f32_e32 v143, v143
	s_nop 0
	v_pk_mul_f32 v[130:131], v[130:131], v[136:137]
	v_pk_mul_f32 v[138:139], v[138:139], v[142:143]
	v_pk_mul_f32 v[130:131], v[134:135], v[130:131]
	v_pk_mul_f32 v[138:139], v[140:141], v[138:139]
	v_cvt_pk_bf16_f32 v148, v130, v131
	v_cvt_pk_bf16_f32 v149, v138, v139
	v_pk_mul_f32 v[130:131], v[4:5], v[164:165] op_sel_hi:[1,0]
	v_pk_mul_f32 v[138:139], v[6:7], v[164:165] op_sel_hi:[1,0]
	v_pk_mul_f32 v[134:135], v[12:13], v[164:165] op_sel_hi:[1,0]
	v_pk_mul_f32 v[140:141], v[14:15], v[164:165] op_sel_hi:[1,0]
	v_mul_f32_e32 v136, 0xbfb8aa3b, v130
	v_mul_f32_e32 v137, 0xbfb8aa3b, v131
	v_mul_f32_e32 v142, 0xbfb8aa3b, v138
	v_mul_f32_e32 v143, 0xbfb8aa3b, v139
	v_exp_f32_e32 v136, v136
	v_exp_f32_e32 v137, v137
	v_exp_f32_e32 v142, v142
	v_exp_f32_e32 v143, v143
	v_add_f32_e32 v136, 1.0, v136
	v_add_f32_e32 v137, 1.0, v137
	v_add_f32_e32 v142, 1.0, v142
	v_add_f32_e32 v143, 1.0, v143
	v_rcp_f32_e32 v136, v136
	v_rcp_f32_e32 v137, v137
	v_rcp_f32_e32 v142, v142
	v_rcp_f32_e32 v143, v143
	s_nop 0
	v_pk_mul_f32 v[130:131], v[130:131], v[136:137]
	v_pk_mul_f32 v[138:139], v[138:139], v[142:143]
	v_pk_mul_f32 v[130:131], v[134:135], v[130:131]
	v_pk_mul_f32 v[138:139], v[140:141], v[138:139]
	v_cvt_pk_bf16_f32 v150, v130, v131
	v_cvt_pk_bf16_f32 v151, v138, v139
	s_nop 1
	v_permlane16_swap_b32_e32 v148, v150
	v_permlane16_swap_b32_e32 v149, v151
	global_store_dwordx4 v[132:133], v[148:151], off

; __device__ __forceinline__ void gemm_phase(const GemmArgs& a, char* smem) {
;     ...
;     if (emode == 0) {
; #pragma unroll
;       for (int ai = 0; ai < 2; ++ai)
; #pragma unroll
;         for (int m = 0; m < 4; ++m) {
;           const int row = brow + ai * 128 + wr * 64 + m * 16 + fr;
;           const float r = rr[ai][m];
; #pragma unroll
;           for (int bj = 0; bj < 2; ++bj)
; #pragma unroll
;             for (int n = 0; n < 2; ++n) {
;               const int col = bcol + bj * 128 + wc * 32 + n * 16 + fq * 4;
;               if (col < a.ncols) {
;                 uint2 pk;
;                 pk.x = pack2(acc[ai][bj][m][n][0] * r, acc[ai][bj][m][n][1] * r);
;                 pk.y = pack2(acc[ai][bj][m][n][2] * r, acc[ai][bj][m][n][3] * r);
;                 *(uint2*)(a.outb + (long)row * a.ldo + col) = pk;
;               }
;             }
;         }
.LBB0_261:
	s_andn2_b64 vcc, exec, s[6:7]
	s_cbranch_vccnz .LBB0_299
	v_readlane_b32 s2, v251, 59
	v_lshlrev_b32_e32 v128, 5, v190
	v_and_b32_e32 v129, 1, v189
	v_lshrrev_b32_e32 v130, 1, v189
	v_lshlrev_b32_e32 v129, 4, v129
	v_lshl_add_u32 v129, v130, 3, v129
	v_add3_u32 v128, v128, s56, v129
	v_add_u32_e32 v130, 0x80, v128
	v_cmp_gt_i32_e32 vcc, s2, v128
	v_cmp_gt_i32_e64 s[6:7], s2, v130
	v_ashrrev_i32_e32 v129, 31, v128
	v_mad_i64_i32 v[132:133], s[2:3], s82, v158, 0
	v_lshl_add_u64 v[132:133], v[132:133], 1, s[60:61]
	v_lshl_add_u64 v[132:133], v[128:129], 1, v[132:133]
	s_mov_b64 s[50:51], exec
	s_and_b64 s[2:3], vcc, exec
	s_and_b64 s[6:7], s[6:7], exec
	s_lshl_b32 s8, s82, 5
	s_mov_b32 s9, 0
	v_pk_mul_f32 v[134:135], v[116:117], v[156:157] op_sel:[0,1]
	v_pk_mul_f32 v[136:137], v[118:119], v[156:157] op_sel:[0,1]
	v_pk_mul_f32 v[138:139], v[112:113], v[156:157] op_sel:[0,1]
	v_pk_mul_f32 v[140:141], v[114:115], v[156:157] op_sel:[0,1]
	v_cvt_pk_bf16_f32 v144, v134, v135
	v_cvt_pk_bf16_f32 v145, v136, v137
	v_cvt_pk_bf16_f32 v146, v138, v139
	v_cvt_pk_bf16_f32 v147, v140, v141
	s_nop 1
	v_permlane16_swap_b32_e32 v144, v146
	v_permlane16_swap_b32_e32 v145, v147
	s_mov_b64 exec, s[2:3]
	global_store_dwordx4 v[132:133], v[144:147], off
	s_mov_b64 exec, s[50:51]
	v_pk_mul_f32 v[198:199], v[124:125], v[156:157] op_sel:[0,1]
	v_pk_mul_f32 v[200:201], v[126:127], v[156:157] op_sel:[0,1]
	v_pk_mul_f32 v[202:203], v[120:121], v[156:157] op_sel:[0,1]
	v_pk_mul_f32 v[204:205], v[122:123], v[156:157] op_sel:[0,1]
	v_cvt_pk_bf16_f32 v148, v198, v199
	v_cvt_pk_bf16_f32 v149, v200, v201
	v_cvt_pk_bf16_f32 v150, v202, v203
	v_cvt_pk_bf16_f32 v151, v204, v205
	s_nop 1
	v_permlane16_swap_b32_e32 v148, v150
	v_permlane16_swap_b32_e32 v149, v151
	s_mov_b64 exec, s[6:7]
	global_store_dwordx4 v[132:133], v[148:151], off offset:256
	s_mov_b64 exec, s[50:51]
	v_lshl_add_u64 v[132:133], v[132:133], 0, s[8:9]
	v_pk_mul_f32 v[134:135], v[96:97], v[156:157] op_sel_hi:[1,0]
	v_pk_mul_f32 v[136:137], v[98:99], v[156:157] op_sel_hi:[1,0]
	v_pk_mul_f32 v[138:139], v[100:101], v[156:157] op_sel_hi:[1,0]
	v_pk_mul_f32 v[140:141], v[102:103], v[156:157] op_sel_hi:[1,0]
	v_cvt_pk_bf16_f32 v144, v134, v135
	v_cvt_pk_bf16_f32 v145, v136, v137
	v_cvt_pk_bf16_f32 v146, v138, v139
	v_cvt_pk_bf16_f32 v147, v140, v141
	s_nop 1
	v_permlane16_swap_b32_e32 v144, v146
	v_permlane16_swap_b32_e32 v145, v147
	s_mov_b64 exec, s[2:3]
	global_store_dwordx4 v[132:133], v[144:147], off
	s_mov_b64 exec, s[50:51]
	v_pk_mul_f32 v[198:199], v[104:105], v[156:157] op_sel_hi:[1,0]
	v_pk_mul_f32 v[200:201], v[106:107], v[156:157] op_sel_hi:[1,0]
	v_pk_mul_f32 v[202:203], v[108:109], v[156:157] op_sel_hi:[1,0]
	v_pk_mul_f32 v[204:205], v[110:111], v[156:157] op_sel_hi:[1,0]
	v_cvt_pk_bf16_f32 v148, v198, v199
	v_cvt_pk_bf16_f32 v149, v200, v201
	v_cvt_pk_bf16_f32 v150, v202, v203
	v_cvt_pk_bf16_f32 v151, v204, v205
	s_nop 1
	v_permlane16_swap_b32_e32 v148, v150
	v_permlane16_swap_b32_e32 v149, v151
	s_mov_b64 exec, s[6:7]
	global_store_dwordx4 v[132:133], v[148:151], off offset:256
	s_mov_b64 exec, s[50:51]
	v_lshl_add_u64 v[132:133], v[132:133], 0, s[8:9]
	v_pk_mul_f32 v[134:135], v[80:81], v[160:161] op_sel:[0,1]
	v_pk_mul_f32 v[136:137], v[82:83], v[160:161] op_sel:[0,1]
	v_pk_mul_f32 v[138:139], v[84:85], v[160:161] op_sel:[0,1]
	v_pk_mul_f32 v[140:141], v[86:87], v[160:161] op_sel:[0,1]
	v_cvt_pk_bf16_f32 v144, v134, v135
	v_cvt_pk_bf16_f32 v145, v136, v137
	v_cvt_pk_bf16_f32 v146, v138, v139
	v_cvt_pk_bf16_f32 v147, v140, v141
	s_nop 1
	v_permlane16_swap_b32_e32 v144, v146
	v_permlane16_swap_b32_e32 v145, v147
	s_mov_b64 exec, s[2:3]
	global_store_dwordx4 v[132:133], v[144:147], off
	s_mov_b64 exec, s[50:51]
	v_pk_mul_f32 v[198:199], v[88:89], v[160:161] op_sel:[0,1]
	v_pk_mul_f32 v[200:201], v[90:91], v[160:161] op_sel:[0,1]
	v_pk_mul_f32 v[202:203], v[92:93], v[160:161] op_sel:[0,1]
	v_pk_mul_f32 v[204:205], v[94:95], v[160:161] op_sel:[0,1]
	v_cvt_pk_bf16_f32 v148, v198, v199
	v_cvt_pk_bf16_f32 v149, v200, v201
	v_cvt_pk_bf16_f32 v150, v202, v203
	v_cvt_pk_bf16_f32 v151, v204, v205
	s_nop 1
	v_permlane16_swap_b32_e32 v148, v150
	v_permlane16_swap_b32_e32 v149, v151
	s_mov_b64 exec, s[6:7]
	global_store_dwordx4 v[132:133], v[148:151], off offset:256
	s_mov_b64 exec, s[50:51]
	v_lshl_add_u64 v[132:133], v[132:133], 0, s[8:9]
	v_pk_mul_f32 v[134:135], v[64:65], v[160:161] op_sel_hi:[1,0]
	v_pk_mul_f32 v[136:137], v[66:67], v[160:161] op_sel_hi:[1,0]
	v_pk_mul_f32 v[138:139], v[68:69], v[160:161] op_sel_hi:[1,0]
	v_pk_mul_f32 v[140:141], v[70:71], v[160:161] op_sel_hi:[1,0]
	v_cvt_pk_bf16_f32 v144, v134, v135
	v_cvt_pk_bf16_f32 v145, v136, v137
	v_cvt_pk_bf16_f32 v146, v138, v139
	v_cvt_pk_bf16_f32 v147, v140, v141
	s_nop 1
	v_permlane16_swap_b32_e32 v144, v146
	v_permlane16_swap_b32_e32 v145, v147
	s_mov_b64 exec, s[2:3]
	global_store_dwordx4 v[132:133], v[144:147], off
	s_mov_b64 exec, s[50:51]
	v_pk_mul_f32 v[198:199], v[72:73], v[160:161] op_sel_hi:[1,0]
	v_pk_mul_f32 v[200:201], v[74:75], v[160:161] op_sel_hi:[1,0]
	v_pk_mul_f32 v[202:203], v[76:77], v[160:161] op_sel_hi:[1,0]
	v_pk_mul_f32 v[204:205], v[78:79], v[160:161] op_sel_hi:[1,0]
	v_cvt_pk_bf16_f32 v148, v198, v199
	v_cvt_pk_bf16_f32 v149, v200, v201
	v_cvt_pk_bf16_f32 v150, v202, v203
; __device__ __forceinline__ void gemm_phase(const GemmArgs& a, char* smem) {
;     ...
;     if (emode == 0) {
; #pragma unroll
;       for (int ai = 0; ai < 2; ++ai)
; #pragma unroll
;         for (int m = 0; m < 4; ++m) {
;           const int row = brow + ai * 128 + wr * 64 + m * 16 + fr;
;           const float r = rr[ai][m];
; #pragma unroll
;           for (int bj = 0; bj < 2; ++bj)
; #pragma unroll
;             for (int n = 0; n < 2; ++n) {
;               const int col = bcol + bj * 128 + wc * 32 + n * 16 + fq * 4;
;               if (col < a.ncols) {
;                 uint2 pk;
;                 pk.x = pack2(acc[ai][bj][m][n][0] * r, acc[ai][bj][m][n][1] * r);
;                 pk.y = pack2(acc[ai][bj][m][n][2] * r, acc[ai][bj][m][n][3] * r);
;                 *(uint2*)(a.outb + (long)row * a.ldo + col) = pk;
;               }
;             }
;         }
	v_cvt_pk_bf16_f32 v151, v204, v205
	s_nop 1
	v_permlane16_swap_b32_e32 v148, v150
	v_permlane16_swap_b32_e32 v149, v151
	s_mov_b64 exec, s[6:7]
	global_store_dwordx4 v[132:133], v[148:151], off offset:256
	s_mov_b64 exec, s[50:51]
	v_lshl_add_u64 v[132:133], v[132:133], 0, s[8:9]
	v_lshl_add_u64 v[132:133], v[132:133], 0, s[8:9]
	v_lshl_add_u64 v[132:133], v[132:133], 0, s[8:9]
	v_lshl_add_u64 v[132:133], v[132:133], 0, s[8:9]
	v_lshl_add_u64 v[132:133], v[132:133], 0, s[8:9]
	v_pk_mul_f32 v[134:135], v[48:49], v[162:163] op_sel:[0,1]
	v_pk_mul_f32 v[136:137], v[50:51], v[162:163] op_sel:[0,1]
	v_pk_mul_f32 v[138:139], v[52:53], v[162:163] op_sel:[0,1]
	v_pk_mul_f32 v[140:141], v[54:55], v[162:163] op_sel:[0,1]
	v_cvt_pk_bf16_f32 v144, v134, v135
	v_cvt_pk_bf16_f32 v145, v136, v137
	v_cvt_pk_bf16_f32 v146, v138, v139
	v_cvt_pk_bf16_f32 v147, v140, v141
	s_nop 1
	v_permlane16_swap_b32_e32 v144, v146
	v_permlane16_swap_b32_e32 v145, v147
	s_mov_b64 exec, s[2:3]
	global_store_dwordx4 v[132:133], v[144:147], off
	s_mov_b64 exec, s[50:51]
	v_pk_mul_f32 v[198:199], v[56:57], v[162:163] op_sel:[0,1]
	v_pk_mul_f32 v[200:201], v[58:59], v[162:163] op_sel:[0,1]
	v_pk_mul_f32 v[202:203], v[60:61], v[162:163] op_sel:[0,1]
	v_pk_mul_f32 v[204:205], v[62:63], v[162:163] op_sel:[0,1]
	v_cvt_pk_bf16_f32 v148, v198, v199
	v_cvt_pk_bf16_f32 v149, v200, v201
	v_cvt_pk_bf16_f32 v150, v202, v203
	v_cvt_pk_bf16_f32 v151, v204, v205
	s_nop 1
	v_permlane16_swap_b32_e32 v148, v150
	v_permlane16_swap_b32_e32 v149, v151
	s_mov_b64 exec, s[6:7]
	global_store_dwordx4 v[132:133], v[148:151], off offset:256
	s_mov_b64 exec, s[50:51]
	v_lshl_add_u64 v[132:133], v[132:133], 0, s[8:9]
	v_pk_mul_f32 v[134:135], v[32:33], v[162:163] op_sel_hi:[1,0]
	v_pk_mul_f32 v[136:137], v[34:35], v[162:163] op_sel_hi:[1,0]
	v_pk_mul_f32 v[138:139], v[36:37], v[162:163] op_sel_hi:[1,0]
	v_pk_mul_f32 v[140:141], v[38:39], v[162:163] op_sel_hi:[1,0]
	v_cvt_pk_bf16_f32 v144, v134, v135
	v_cvt_pk_bf16_f32 v145, v136, v137
	v_cvt_pk_bf16_f32 v146, v138, v139
	v_cvt_pk_bf16_f32 v147, v140, v141
	s_nop 1
	v_permlane16_swap_b32_e32 v144, v146
	v_permlane16_swap_b32_e32 v145, v147
	s_mov_b64 exec, s[2:3]
	global_store_dwordx4 v[132:133], v[144:147], off
	s_mov_b64 exec, s[50:51]
	v_pk_mul_f32 v[198:199], v[40:41], v[162:163] op_sel_hi:[1,0]
	v_pk_mul_f32 v[200:201], v[42:43], v[162:163] op_sel_hi:[1,0]
	v_pk_mul_f32 v[202:203], v[44:45], v[162:163] op_sel_hi:[1,0]
	v_pk_mul_f32 v[204:205], v[46:47], v[162:163] op_sel_hi:[1,0]
	v_cvt_pk_bf16_f32 v148, v198, v199
	v_cvt_pk_bf16_f32 v149, v200, v201
	v_cvt_pk_bf16_f32 v150, v202, v203
	v_cvt_pk_bf16_f32 v151, v204, v205
	s_nop 1
	v_permlane16_swap_b32_e32 v148, v150
	v_permlane16_swap_b32_e32 v149, v151
	s_mov_b64 exec, s[6:7]
	global_store_dwordx4 v[132:133], v[148:151], off offset:256
	s_mov_b64 exec, s[50:51]
	v_lshl_add_u64 v[132:133], v[132:133], 0, s[8:9]
	v_pk_mul_f32 v[134:135], v[16:17], v[164:165] op_sel:[0,1]
	v_pk_mul_f32 v[136:137], v[18:19], v[164:165] op_sel:[0,1]
	v_pk_mul_f32 v[138:139], v[20:21], v[164:165] op_sel:[0,1]
	v_pk_mul_f32 v[140:141], v[22:23], v[164:165] op_sel:[0,1]
	v_cvt_pk_bf16_f32 v144, v134, v135
	v_cvt_pk_bf16_f32 v145, v136, v137
	v_cvt_pk_bf16_f32 v146, v138, v139
	v_cvt_pk_bf16_f32 v147, v140, v141
	s_nop 1
	v_permlane16_swap_b32_e32 v144, v146
	v_permlane16_swap_b32_e32 v145, v147
	s_mov_b64 exec, s[2:3]
	global_store_dwordx4 v[132:133], v[144:147], off
	s_mov_b64 exec, s[50:51]
	v_pk_mul_f32 v[198:199], v[24:25], v[164:165] op_sel:[0,1]
	v_pk_mul_f32 v[200:201], v[26:27], v[164:165] op_sel:[0,1]
	v_pk_mul_f32 v[202:203], v[28:29], v[164:165] op_sel:[0,1]
	v_pk_mul_f32 v[204:205], v[30:31], v[164:165] op_sel:[0,1]
	v_cvt_pk_bf16_f32 v148, v198, v199
	v_cvt_pk_bf16_f32 v149, v200, v201
	v_cvt_pk_bf16_f32 v150, v202, v203
	v_cvt_pk_bf16_f32 v151, v204, v205
	s_nop 1
	v_permlane16_swap_b32_e32 v148, v150
	v_permlane16_swap_b32_e32 v149, v151
	s_mov_b64 exec, s[6:7]
	global_store_dwordx4 v[132:133], v[148:151], off offset:256
	s_mov_b64 exec, s[50:51]
	v_lshl_add_u64 v[132:133], v[132:133], 0, s[8:9]
	v_pk_mul_f32 v[134:135], v[0:1], v[164:165] op_sel_hi:[1,0]
	v_pk_mul_f32 v[136:137], v[2:3], v[164:165] op_sel_hi:[1,0]
	v_pk_mul_f32 v[138:139], v[4:5], v[164:165] op_sel_hi:[1,0]
	v_pk_mul_f32 v[140:141], v[6:7], v[164:165] op_sel_hi:[1,0]
	v_cvt_pk_bf16_f32 v144, v134, v135
	v_cvt_pk_bf16_f32 v145, v136, v137
	v_cvt_pk_bf16_f32 v146, v138, v139
	v_cvt_pk_bf16_f32 v147, v140, v141
	s_nop 1
	v_permlane16_swap_b32_e32 v144, v146
	v_permlane16_swap_b32_e32 v145, v147
	s_mov_b64 exec, s[2:3]
	global_store_dwordx4 v[132:133], v[144:147], off
	s_mov_b64 exec, s[50:51]
	v_pk_mul_f32 v[198:199], v[8:9], v[164:165] op_sel_hi:[1,0]
	v_pk_mul_f32 v[200:201], v[10:11], v[164:165] op_sel_hi:[1,0]
	v_pk_mul_f32 v[202:203], v[12:13], v[164:165] op_sel_hi:[1,0]
	v_pk_mul_f32 v[204:205], v[14:15], v[164:165] op_sel_hi:[1,0]
	v_cvt_pk_bf16_f32 v148, v198, v199
	v_cvt_pk_bf16_f32 v149, v200, v201
	v_cvt_pk_bf16_f32 v150, v202, v203
	v_cvt_pk_bf16_f32 v151, v204, v205
	s_nop 1
	v_permlane16_swap_b32_e32 v148, v150
	v_permlane16_swap_b32_e32 v149, v151
	s_mov_b64 exec, s[6:7]
	global_store_dwordx4 v[132:133], v[148:151], off offset:256
	s_mov_b64 exec, s[50:51]

;   __device__ __forceinline__ bf16* z() const { return (bf16*)(ws + OFF_z); }
; __device__ __forceinline__ void gemm_phase(const GemmArgs& a, char* smem) {
;     ...
; #pragma unroll
;         for (int r = 0; r < 2; ++r) {
;           const int k = 2 * hf + r;
;           const int roff = ai * 128 + m * 16 + k;
;           const f32x4 av = *(const f32x4*)(reg + ((lrd + k * 1024) ^ (k << 4)));
;           float4 v = xv[un & 1][r];
;           v.x += av[0]; v.y += av[1]; v.z += av[2]; v.w += av[3];
;           *(float4*)(xoutb + (long)roff * 1024) = v;
;           if (xbb) {
;             uint2 pk;
;             pk.x = pack2(v.x, v.y);
;             pk.y = pack2(v.z, v.w);
;             *(uint2*)(xbb + (long)roff * 1024) = pk;
;           }
;           if (ssnb) {
;             float part = (v.x * v.x + v.y * v.y) + (v.z * v.z + v.w * v.w);
; #pragma unroll
;             for (int o = 32; o >= 1; o >>= 1) part += __shfl_xor(part, o);
;             if (ln == 0) ssnb[roff * 4] = part;
;           }
;         }
.LBB0_303:
	s_lshl_b64 s[2:3], s[6:7], 4
	v_readlane_b32 s6, v251, 49
	v_readlane_b32 s7, v251, 50
	s_add_u32 s6, s6, s2
	s_addc_u32 s7, s7, s3
	s_ashr_i32 s2, s56, 8
	s_ashr_i32 s3, s2, 31
	s_lshl_b64 s[2:3], s[2:3], 2
	s_add_u32 s56, s6, s2
	s_addc_u32 s57, s7, s3
	v_readlane_b32 s2, v250, 19
	v_readlane_b32 s3, v250, 20
	v_cmp_eq_u32_e64 s[6:7], 0, v134
	s_andn2_b64 vcc, exec, s[2:3]
	v_cndmask_b32_e64 v124, 0, 1, s[2:3]
	v_cmp_ne_u32_e64 s[10:11], 1, v124
	s_cbranch_vccnz .LBB0_307
	v_pk_mul_f32 v[116:117], v[116:117], v[116:117]
	v_pk_mul_f32 v[118:119], v[118:119], v[118:119]
	v_add_f32_e32 v116, v116, v117
	v_add_f32_e32 v118, v118, v119
	v_add_f32_e32 v116, v116, v118
	s_nop 1
	v_add_f32_dpp v116, v116, v116 quad_perm:[1,0,3,2] row_mask:0xf bank_mask:0xf
	s_nop 1
	v_add_f32_dpp v116, v116, v116 quad_perm:[2,3,0,1] row_mask:0xf bank_mask:0xf
	s_nop 1
	v_add_f32_dpp v116, v116, v116 row_half_mirror row_mask:0xf bank_mask:0xf
	s_nop 1
	v_add_f32_dpp v116, v116, v116 row_mirror row_mask:0xf bank_mask:0xf
	s_nop 1
	v_add_f32_dpp v116, v116, v116 row_bcast:15 row_mask:0xa bank_mask:0xf
	s_nop 1
	v_add_f32_dpp v116, v116, v116 row_bcast:31 row_mask:0xc bank_mask:0xf
	s_mov_b64 s[68:69], exec
	s_lshl_b64 exec, 1, 63
	global_store_dword v153, v116, s[56:57]
	s_mov_b64 exec, s[68:69]
.LBB0_306:
.LBB0_307:
	v_xor_b32_e32 v139, 16, v138
	s_waitcnt lgkmcnt(0)
	ds_read_b128 v[116:119], v139 offset:33792
	v_lshl_add_u64 v[134:135], s[50:51], 0, v[152:153]
	v_add_co_u32_e32 v124, vcc, 0x1000, v134
	s_waitcnt lgkmcnt(0)
	v_pk_add_f32 v[116:117], v[128:129], v[116:117]
	v_addc_co_u32_e32 v125, vcc, 0, v135, vcc
	v_pk_add_f32 v[118:119], v[130:131], v[118:119]
	s_and_b64 vcc, exec, s[8:9]
	global_store_dwordx4 v[124:125], v[116:119], off
	s_cbranch_vccnz .LBB0_309
	v_cvt_pk_bf16_f32 v124, v116, v117
	v_cvt_pk_bf16_f32 v125, v118, v119
	global_store_dwordx2 v[132:133], v[124:125], off offset:2048
.LBB0_309:
	s_and_b64 vcc, exec, s[10:11]
	s_cbranch_vccnz .LBB0_313
	v_pk_mul_f32 v[116:117], v[116:117], v[116:117]
	v_pk_mul_f32 v[118:119], v[118:119], v[118:119]
	v_add_f32_e32 v116, v116, v117
	v_add_f32_e32 v118, v118, v119
	v_add_f32_e32 v116, v116, v118
	s_nop 1
	v_add_f32_dpp v116, v116, v116 quad_perm:[1,0,3,2] row_mask:0xf bank_mask:0xf
	s_nop 1
	v_add_f32_dpp v116, v116, v116 quad_perm:[2,3,0,1] row_mask:0xf bank_mask:0xf
	s_nop 1
	v_add_f32_dpp v116, v116, v116 row_half_mirror row_mask:0xf bank_mask:0xf
	s_nop 1
	v_add_f32_dpp v116, v116, v116 row_mirror row_mask:0xf bank_mask:0xf
	s_nop 1
	v_add_f32_dpp v116, v116, v116 row_bcast:15 row_mask:0xa bank_mask:0xf
	s_nop 1
	v_add_f32_dpp v116, v116, v116 row_bcast:31 row_mask:0xc bank_mask:0xf
	s_mov_b64 s[50:51], exec
	s_lshl_b64 exec, 1, 63
	global_store_dword v153, v116, s[56:57] offset:16
	s_mov_b64 exec, s[50:51]
.LBB0_312:
.LBB0_313:
	v_add_co_u32_e32 v116, vcc, 0x10000, v136
	v_xor_b32_e32 v128, 32, v138
	s_waitcnt lgkmcnt(0)
	v_addc_co_u32_e32 v117, vcc, 0, v137, vcc
	v_add_co_u32_e32 v118, vcc, 0x11000, v136
	s_nop 1
	v_addc_co_u32_e32 v119, vcc, 0, v137, vcc
	global_load_dwordx4 v[124:127], v[116:117], off
	s_nop 0
	global_load_dwordx4 v[116:119], v[118:119], off
	ds_read_b128 v[160:163], v128 offset:34816
	v_add_co_u32_e32 v130, vcc, 0x2000, v134
	s_waitcnt vmcnt(5) lgkmcnt(0)
	v_pk_add_f32 v[120:121], v[120:121], v[160:161]
	v_addc_co_u32_e32 v131, vcc, 0, v135, vcc
	v_pk_add_f32 v[122:123], v[122:123], v[162:163]
	s_and_b64 vcc, exec, s[8:9]
	global_store_dwordx4 v[130:131], v[120:123], off
	s_cbranch_vccnz .LBB0_315
	v_add_co_u32_e32 v160, vcc, 0x1000, v132
	v_cvt_pk_bf16_f32 v130, v120, v121
	v_cvt_pk_bf16_f32 v131, v122, v123
	v_addc_co_u32_e32 v161, vcc, 0, v133, vcc
	global_store_dwordx2 v[160:161], v[130:131], off
.LBB0_315:
	s_and_b64 vcc, exec, s[10:11]
	s_cbranch_vccnz .LBB0_319
	v_pk_mul_f32 v[120:121], v[120:121], v[120:121]
	v_pk_mul_f32 v[122:123], v[122:123], v[122:123]
	v_add_f32_e32 v120, v120, v121
	v_add_f32_e32 v122, v122, v123
	v_add_f32_e32 v120, v120, v122
	s_nop 1
	v_add_f32_dpp v120, v120, v120 quad_perm:[1,0,3,2] row_mask:0xf bank_mask:0xf
	s_nop 1
	v_add_f32_dpp v120, v120, v120 quad_perm:[2,3,0,1] row_mask:0xf bank_mask:0xf
	s_nop 1
	v_add_f32_dpp v120, v120, v120 row_half_mirror row_mask:0xf bank_mask:0xf
	s_nop 1
	v_add_f32_dpp v120, v120, v120 row_mirror row_mask:0xf bank_mask:0xf
	s_nop 1
	v_add_f32_dpp v120, v120, v120 row_bcast:15 row_mask:0xa bank_mask:0xf
	s_nop 1
	v_add_f32_dpp v120, v120, v120 row_bcast:31 row_mask:0xc bank_mask:0xf
	s_mov_b64 s[50:51], exec
	s_lshl_b64 exec, 1, 63
	global_store_dword v153, v120, s[56:57] offset:32
	s_mov_b64 exec, s[50:51]
.LBB0_318:
.LBB0_319:
	v_xor_b32_e32 v120, 48, v138
	ds_read_b128 v[160:163], v120 offset:35840
	v_add_co_u32_e32 v122, vcc, 0x3000, v134
	s_waitcnt vmcnt(5) lgkmcnt(0)
	v_pk_add_f32 v[112:113], v[112:113], v[160:161]
	v_addc_co_u32_e32 v123, vcc, 0, v135, vcc
	v_pk_add_f32 v[114:115], v[114:115], v[162:163]
	s_and_b64 vcc, exec, s[8:9]
	global_store_dwordx4 v[122:123], v[112:115], off
	s_cbranch_vccnz .LBB0_321
	v_add_co_u32_e32 v130, vcc, 0x1000, v132
	v_cvt_pk_bf16_f32 v122, v112, v113
	v_cvt_pk_bf16_f32 v123, v114, v115
	v_addc_co_u32_e32 v131, vcc, 0, v133, vcc
	global_store_dwordx2 v[130:131], v[122:123], off offset:2048
;   __device__ __forceinline__ bf16* z() const { return (bf16*)(ws + OFF_z); }
; __device__ __forceinline__ void gemm_phase(const GemmArgs& a, char* smem) {
;     ...
; #pragma unroll
;         for (int r = 0; r < 2; ++r) {
;           const int k = 2 * hf + r;
;           const int roff = ai * 128 + m * 16 + k;
;           const f32x4 av = *(const f32x4*)(reg + ((lrd + k * 1024) ^ (k << 4)));
;           float4 v = xv[un & 1][r];
;           v.x += av[0]; v.y += av[1]; v.z += av[2]; v.w += av[3];
;           *(float4*)(xoutb + (long)roff * 1024) = v;
;           if (xbb) {
;             uint2 pk;
;             pk.x = pack2(v.x, v.y);
;             pk.y = pack2(v.z, v.w);
;             *(uint2*)(xbb + (long)roff * 1024) = pk;
;           }
;           if (ssnb) {
;             float part = (v.x * v.x + v.y * v.y) + (v.z * v.z + v.w * v.w);
; #pragma unroll
;             for (int o = 32; o >= 1; o >>= 1) part += __shfl_xor(part, o);
;             if (ln == 0) ssnb[roff * 4] = part;
;           }
;         }
.LBB0_321:
	s_and_b64 vcc, exec, s[10:11]
	s_cbranch_vccnz .LBB0_325
	v_pk_mul_f32 v[112:113], v[112:113], v[112:113]
	v_pk_mul_f32 v[114:115], v[114:115], v[114:115]
	v_add_f32_e32 v112, v112, v113
	v_add_f32_e32 v114, v114, v115
	v_add_f32_e32 v112, v112, v114
	s_nop 1
	v_add_f32_dpp v112, v112, v112 quad_perm:[1,0,3,2] row_mask:0xf bank_mask:0xf
	s_nop 1
	v_add_f32_dpp v112, v112, v112 quad_perm:[2,3,0,1] row_mask:0xf bank_mask:0xf
	s_nop 1
	v_add_f32_dpp v112, v112, v112 row_half_mirror row_mask:0xf bank_mask:0xf
	s_nop 1
	v_add_f32_dpp v112, v112, v112 row_mirror row_mask:0xf bank_mask:0xf
	s_nop 1
	v_add_f32_dpp v112, v112, v112 row_bcast:15 row_mask:0xa bank_mask:0xf
	s_nop 1
	v_add_f32_dpp v112, v112, v112 row_bcast:31 row_mask:0xc bank_mask:0xf
	s_mov_b64 s[50:51], exec
	s_lshl_b64 exec, 1, 63
	global_store_dword v153, v112, s[56:57] offset:48
	s_mov_b64 exec, s[50:51]
.LBB0_324:
.LBB0_325:
	s_mov_b32 s2, 0x18000
	v_add3_u32 v115, v157, v158, s2
	v_add_u32_e32 v112, v115, v141
	ds_write_b128 v112, v[96:99]
	v_add_co_u32_e32 v96, vcc, 0x12000, v136
	s_waitcnt lgkmcnt(1)
	v_add_u32_e32 v113, v115, v142
	v_add_u32_e32 v114, v115, v143
	v_add_u32_e32 v115, v115, v156
	v_addc_co_u32_e32 v97, vcc, 0, v137, vcc
	ds_write_b128 v113, v[100:103]
	ds_write_b128 v114, v[104:107]
	ds_write_b128 v115, v[108:111]
	v_add_co_u32_e32 v98, vcc, 0x13000, v136
	s_waitcnt lgkmcnt(0)
	s_barrier
	s_nop 0
	v_addc_co_u32_e32 v99, vcc, 0, v137, vcc
	global_load_dwordx4 v[108:111], v[96:97], off
	global_load_dwordx4 v[100:103], v[98:99], off
	v_add_u32_e32 v121, 0x18000, v138
	ds_read_b128 v[96:99], v121
	v_add_co_u32_e32 v104, vcc, 0x10000, v134
	s_waitcnt vmcnt(5) lgkmcnt(0)
	v_pk_add_f32 v[96:97], v[124:125], v[96:97]
	v_addc_co_u32_e32 v105, vcc, 0, v135, vcc
	v_pk_add_f32 v[98:99], v[126:127], v[98:99]
	s_and_b64 vcc, exec, s[8:9]
	global_store_dwordx4 v[104:105], v[96:99], off
	s_cbranch_vccnz .LBB0_327
	v_add_co_u32_e32 v106, vcc, 0x8000, v132
	v_cvt_pk_bf16_f32 v104, v96, v97
	v_cvt_pk_bf16_f32 v105, v98, v99
	v_addc_co_u32_e32 v107, vcc, 0, v133, vcc
	global_store_dwordx2 v[106:107], v[104:105], off
.LBB0_327:
	s_and_b64 vcc, exec, s[10:11]
	s_cbranch_vccnz .LBB0_331
	v_pk_mul_f32 v[96:97], v[96:97], v[96:97]
	v_pk_mul_f32 v[98:99], v[98:99], v[98:99]
	v_add_f32_e32 v96, v96, v97
	v_add_f32_e32 v98, v98, v99
	v_add_f32_e32 v96, v96, v98
	s_nop 1
	v_add_f32_dpp v96, v96, v96 quad_perm:[1,0,3,2] row_mask:0xf bank_mask:0xf
	s_nop 1
	v_add_f32_dpp v96, v96, v96 quad_perm:[2,3,0,1] row_mask:0xf bank_mask:0xf
	s_nop 1
	v_add_f32_dpp v96, v96, v96 row_half_mirror row_mask:0xf bank_mask:0xf
	s_nop 1
	v_add_f32_dpp v96, v96, v96 row_mirror row_mask:0xf bank_mask:0xf
	s_nop 1
	v_add_f32_dpp v96, v96, v96 row_bcast:15 row_mask:0xa bank_mask:0xf
	s_nop 1
	v_add_f32_dpp v96, v96, v96 row_bcast:31 row_mask:0xc bank_mask:0xf
	s_mov_b64 s[50:51], exec
	s_lshl_b64 exec, 1, 63
	global_store_dword v153, v96, s[56:57] offset:256
	s_mov_b64 exec, s[50:51]
.LBB0_330:
.LBB0_331:
	v_xor_b32_e32 v96, 0x410, v138
	v_add_u32_e32 v122, 0x18000, v96
	s_waitcnt lgkmcnt(0)
	ds_read_b128 v[96:99], v122
	v_add_co_u32_e32 v104, vcc, 0x11000, v134
	s_waitcnt vmcnt(5) lgkmcnt(0)
	v_pk_add_f32 v[96:97], v[116:117], v[96:97]
	v_addc_co_u32_e32 v105, vcc, 0, v135, vcc
	v_pk_add_f32 v[98:99], v[118:119], v[98:99]
	s_and_b64 vcc, exec, s[8:9]
	global_store_dwordx4 v[104:105], v[96:99], off
	s_cbranch_vccnz .LBB0_333
	v_add_co_u32_e32 v106, vcc, 0x8000, v132
	v_cvt_pk_bf16_f32 v104, v96, v97
	v_cvt_pk_bf16_f32 v105, v98, v99
	v_addc_co_u32_e32 v107, vcc, 0, v133, vcc
	global_store_dwordx2 v[106:107], v[104:105], off offset:2048
.LBB0_333:
	s_and_b64 vcc, exec, s[10:11]
	s_cbranch_vccnz .LBB0_337
	v_pk_mul_f32 v[96:97], v[96:97], v[96:97]
	v_pk_mul_f32 v[98:99], v[98:99], v[98:99]
	v_add_f32_e32 v96, v96, v97
	v_add_f32_e32 v98, v98, v99
	v_add_f32_e32 v96, v96, v98
	s_nop 1
	v_add_f32_dpp v96, v96, v96 quad_perm:[1,0,3,2] row_mask:0xf bank_mask:0xf
	s_nop 1
	v_add_f32_dpp v96, v96, v96 quad_perm:[2,3,0,1] row_mask:0xf bank_mask:0xf
	s_nop 1
	v_add_f32_dpp v96, v96, v96 row_half_mirror row_mask:0xf bank_mask:0xf
	s_nop 1
	v_add_f32_dpp v96, v96, v96 row_mirror row_mask:0xf bank_mask:0xf
	s_nop 1
	v_add_f32_dpp v96, v96, v96 row_bcast:15 row_mask:0xa bank_mask:0xf
	s_nop 1
	v_add_f32_dpp v96, v96, v96 row_bcast:31 row_mask:0xc bank_mask:0xf
	s_mov_b64 s[50:51], exec
	s_lshl_b64 exec, 1, 63
	global_store_dword v153, v96, s[56:57] offset:272
	s_mov_b64 exec, s[50:51]
.LBB0_336:
.LBB0_337:
	v_add_co_u32_e32 v96, vcc, 0x20000, v136
	v_xor_b32_e32 v116, 0x820, v138
	s_waitcnt lgkmcnt(0)
	v_addc_co_u32_e32 v97, vcc, 0, v137, vcc
	v_add_co_u32_e32 v98, vcc, 0x21000, v136
	v_add_u32_e32 v116, 0x18000, v116
	s_nop 0
	v_addc_co_u32_e32 v99, vcc, 0, v137, vcc
	global_load_dwordx4 v[104:107], v[96:97], off
	s_nop 0
	global_load_dwordx4 v[96:99], v[98:99], off
	ds_read_b128 v[124:127], v116
	v_add_co_u32_e32 v118, vcc, 0x12000, v134
	s_waitcnt vmcnt(5) lgkmcnt(0)
	v_pk_add_f32 v[108:109], v[108:109], v[124:125]
	v_addc_co_u32_e32 v119, vcc, 0, v135, vcc
	v_pk_add_f32 v[110:111], v[110:111], v[126:127]
	s_and_b64 vcc, exec, s[8:9]
	global_store_dwordx4 v[118:119], v[108:111], off
	s_cbranch_vccnz .LBB0_339
	v_add_co_u32_e32 v124, vcc, 0x9000, v132
	v_cvt_pk_bf16_f32 v118, v108, v109
	v_cvt_pk_bf16_f32 v119, v110, v111
	v_addc_co_u32_e32 v125, vcc, 0, v133, vcc
	global_store_dwordx2 v[124:125], v[118:119], off
;   __device__ __forceinline__ bf16* z() const { return (bf16*)(ws + OFF_z); }
; __device__ __forceinline__ void gemm_phase(const GemmArgs& a, char* smem) {
;     ...
; #pragma unroll
;         for (int r = 0; r < 2; ++r) {
;           const int k = 2 * hf + r;
;           const int roff = ai * 128 + m * 16 + k;
;           const f32x4 av = *(const f32x4*)(reg + ((lrd + k * 1024) ^ (k << 4)));
;           float4 v = xv[un & 1][r];
;           v.x += av[0]; v.y += av[1]; v.z += av[2]; v.w += av[3];
;           *(float4*)(xoutb + (long)roff * 1024) = v;
;           if (xbb) {
;             uint2 pk;
;             pk.x = pack2(v.x, v.y);
;             pk.y = pack2(v.z, v.w);
;             *(uint2*)(xbb + (long)roff * 1024) = pk;
;           }
;           if (ssnb) {
;             float part = (v.x * v.x + v.y * v.y) + (v.z * v.z + v.w * v.w);
; #pragma unroll
;             for (int o = 32; o >= 1; o >>= 1) part += __shfl_xor(part, o);
;             if (ln == 0) ssnb[roff * 4] = part;
;           }
;         }
.LBB0_339:
	s_and_b64 vcc, exec, s[10:11]
	s_cbranch_vccnz .LBB0_343
	v_pk_mul_f32 v[108:109], v[108:109], v[108:109]
	v_pk_mul_f32 v[110:111], v[110:111], v[110:111]
	v_add_f32_e32 v108, v108, v109
	v_add_f32_e32 v110, v110, v111
	v_add_f32_e32 v108, v108, v110
	s_nop 1
	v_add_f32_dpp v108, v108, v108 quad_perm:[1,0,3,2] row_mask:0xf bank_mask:0xf
	s_nop 1
	v_add_f32_dpp v108, v108, v108 quad_perm:[2,3,0,1] row_mask:0xf bank_mask:0xf
	s_nop 1
	v_add_f32_dpp v108, v108, v108 row_half_mirror row_mask:0xf bank_mask:0xf
	s_nop 1
	v_add_f32_dpp v108, v108, v108 row_mirror row_mask:0xf bank_mask:0xf
	s_nop 1
	v_add_f32_dpp v108, v108, v108 row_bcast:15 row_mask:0xa bank_mask:0xf
	s_nop 1
	v_add_f32_dpp v108, v108, v108 row_bcast:31 row_mask:0xc bank_mask:0xf
	s_mov_b64 s[50:51], exec
	s_lshl_b64 exec, 1, 63
	global_store_dword v153, v108, s[56:57] offset:288
	s_mov_b64 exec, s[50:51]
.LBB0_342:
.LBB0_343:
	v_xor_b32_e32 v108, 0xc30, v138
	v_add_u32_e32 v108, 0x18000, v108
	ds_read_b128 v[124:127], v108
	v_add_co_u32_e32 v110, vcc, 0x13000, v134
	s_waitcnt vmcnt(5) lgkmcnt(0)
	v_pk_add_f32 v[100:101], v[100:101], v[124:125]
	v_addc_co_u32_e32 v111, vcc, 0, v135, vcc
	v_pk_add_f32 v[102:103], v[102:103], v[126:127]
	s_and_b64 vcc, exec, s[8:9]
	global_store_dwordx4 v[110:111], v[100:103], off
	s_cbranch_vccnz .LBB0_345
	v_add_co_u32_e32 v118, vcc, 0x9000, v132
	v_cvt_pk_bf16_f32 v110, v100, v101
	v_cvt_pk_bf16_f32 v111, v102, v103
	v_addc_co_u32_e32 v119, vcc, 0, v133, vcc
	global_store_dwordx2 v[118:119], v[110:111], off offset:2048
.LBB0_345:
	s_and_b64 vcc, exec, s[10:11]
	s_cbranch_vccnz .LBB0_349
	v_pk_mul_f32 v[100:101], v[100:101], v[100:101]
	v_pk_mul_f32 v[102:103], v[102:103], v[102:103]
	v_add_f32_e32 v100, v100, v101
	v_add_f32_e32 v102, v102, v103
	v_add_f32_e32 v100, v100, v102
	s_nop 1
	v_add_f32_dpp v100, v100, v100 quad_perm:[1,0,3,2] row_mask:0xf bank_mask:0xf
	s_nop 1
	v_add_f32_dpp v100, v100, v100 quad_perm:[2,3,0,1] row_mask:0xf bank_mask:0xf
	s_nop 1
	v_add_f32_dpp v100, v100, v100 row_half_mirror row_mask:0xf bank_mask:0xf
	s_nop 1
	v_add_f32_dpp v100, v100, v100 row_mirror row_mask:0xf bank_mask:0xf
	s_nop 1
	v_add_f32_dpp v100, v100, v100 row_bcast:15 row_mask:0xa bank_mask:0xf
	s_nop 1
	v_add_f32_dpp v100, v100, v100 row_bcast:31 row_mask:0xc bank_mask:0xf
	s_mov_b64 s[50:51], exec
	s_lshl_b64 exec, 1, 63
	global_store_dword v153, v100, s[56:57] offset:304
	s_mov_b64 exec, s[50:51]
.LBB0_348:
.LBB0_349:
	v_add_u32_e32 v100, v140, v141
	ds_write_b128 v100, v[80:83] offset:32768
	v_add_co_u32_e32 v80, vcc, 0x22000, v136
	s_waitcnt lgkmcnt(1)
	v_add_u32_e32 v101, v140, v142
	v_add_u32_e32 v102, v140, v143
	v_add_u32_e32 v103, v140, v156
	v_addc_co_u32_e32 v81, vcc, 0, v137, vcc
	ds_write_b128 v101, v[84:87] offset:32768
	ds_write_b128 v102, v[88:91] offset:32768
	ds_write_b128 v103, v[92:95] offset:32768
	v_add_co_u32_e32 v82, vcc, 0x23000, v136
	s_waitcnt lgkmcnt(0)
	s_barrier
	s_nop 0
	v_addc_co_u32_e32 v83, vcc, 0, v137, vcc
	global_load_dwordx4 v[92:95], v[80:81], off
	global_load_dwordx4 v[84:87], v[82:83], off
	ds_read_b128 v[80:83], v138 offset:32768
	v_add_co_u32_e32 v88, vcc, 0x20000, v134
	s_waitcnt vmcnt(5) lgkmcnt(0)
	v_pk_add_f32 v[80:81], v[104:105], v[80:81]
	v_addc_co_u32_e32 v89, vcc, 0, v135, vcc
	v_pk_add_f32 v[82:83], v[106:107], v[82:83]
	s_and_b64 vcc, exec, s[8:9]
	global_store_dwordx4 v[88:89], v[80:83], off
	s_cbranch_vccnz .LBB0_351
	v_add_co_u32_e32 v90, vcc, 0x10000, v132
	v_cvt_pk_bf16_f32 v88, v80, v81
	v_cvt_pk_bf16_f32 v89, v82, v83
	v_addc_co_u32_e32 v91, vcc, 0, v133, vcc
	global_store_dwordx2 v[90:91], v[88:89], off
.LBB0_351:
	s_and_b64 vcc, exec, s[10:11]
	s_cbranch_vccnz .LBB0_355
	v_pk_mul_f32 v[80:81], v[80:81], v[80:81]
	v_pk_mul_f32 v[82:83], v[82:83], v[82:83]
	v_add_f32_e32 v80, v80, v81
	v_add_f32_e32 v82, v82, v83
	v_add_f32_e32 v80, v80, v82
	s_nop 1
	v_add_f32_dpp v80, v80, v80 quad_perm:[1,0,3,2] row_mask:0xf bank_mask:0xf
	s_nop 1
	v_add_f32_dpp v80, v80, v80 quad_perm:[2,3,0,1] row_mask:0xf bank_mask:0xf
	s_nop 1
	v_add_f32_dpp v80, v80, v80 row_half_mirror row_mask:0xf bank_mask:0xf
	s_nop 1
	v_add_f32_dpp v80, v80, v80 row_mirror row_mask:0xf bank_mask:0xf
	s_nop 1
	v_add_f32_dpp v80, v80, v80 row_bcast:15 row_mask:0xa bank_mask:0xf
	s_nop 1
	v_add_f32_dpp v80, v80, v80 row_bcast:31 row_mask:0xc bank_mask:0xf
	s_mov_b64 s[50:51], exec
	s_lshl_b64 exec, 1, 63
	global_store_dword v153, v80, s[56:57] offset:512
	s_mov_b64 exec, s[50:51]
.LBB0_354:
.LBB0_355:
	s_waitcnt lgkmcnt(0)
	ds_read_b128 v[80:83], v139 offset:33792
	v_add_co_u32_e32 v88, vcc, 0x21000, v134
	s_waitcnt vmcnt(5) lgkmcnt(0)
	v_pk_add_f32 v[80:81], v[96:97], v[80:81]
	v_addc_co_u32_e32 v89, vcc, 0, v135, vcc
	v_pk_add_f32 v[82:83], v[98:99], v[82:83]
	s_and_b64 vcc, exec, s[8:9]
	global_store_dwordx4 v[88:89], v[80:83], off
	s_cbranch_vccnz .LBB0_357
	v_add_co_u32_e32 v90, vcc, 0x10000, v132
	v_cvt_pk_bf16_f32 v88, v80, v81
	v_cvt_pk_bf16_f32 v89, v82, v83
	v_addc_co_u32_e32 v91, vcc, 0, v133, vcc
	global_store_dwordx2 v[90:91], v[88:89], off offset:2048
.LBB0_357:
	s_and_b64 vcc, exec, s[10:11]
	s_cbranch_vccnz .LBB0_361
	v_pk_mul_f32 v[80:81], v[80:81], v[80:81]
	v_pk_mul_f32 v[82:83], v[82:83], v[82:83]
	v_add_f32_e32 v80, v80, v81
	v_add_f32_e32 v82, v82, v83
	v_add_f32_e32 v80, v80, v82
	s_nop 1
	v_add_f32_dpp v80, v80, v80 quad_perm:[1,0,3,2] row_mask:0xf bank_mask:0xf
	s_nop 1
	v_add_f32_dpp v80, v80, v80 quad_perm:[2,3,0,1] row_mask:0xf bank_mask:0xf
	s_nop 1
	v_add_f32_dpp v80, v80, v80 row_half_mirror row_mask:0xf bank_mask:0xf
	s_nop 1
	v_add_f32_dpp v80, v80, v80 row_mirror row_mask:0xf bank_mask:0xf
	s_nop 1
	v_add_f32_dpp v80, v80, v80 row_bcast:15 row_mask:0xa bank_mask:0xf
	s_nop 1
	v_add_f32_dpp v80, v80, v80 row_bcast:31 row_mask:0xc bank_mask:0xf
	s_mov_b64 s[50:51], exec
	s_lshl_b64 exec, 1, 63
	global_store_dword v153, v80, s[56:57] offset:528
	s_mov_b64 exec, s[50:51]
;   __device__ __forceinline__ bf16* z() const { return (bf16*)(ws + OFF_z); }
; __device__ __forceinline__ void gemm_phase(const GemmArgs& a, char* smem) {
;     ...
; #pragma unroll
;         for (int r = 0; r < 2; ++r) {
;           const int k = 2 * hf + r;
;           const int roff = ai * 128 + m * 16 + k;
;           const f32x4 av = *(const f32x4*)(reg + ((lrd + k * 1024) ^ (k << 4)));
;           float4 v = xv[un & 1][r];
;           v.x += av[0]; v.y += av[1]; v.z += av[2]; v.w += av[3];
;           *(float4*)(xoutb + (long)roff * 1024) = v;
;           if (xbb) {
;             uint2 pk;
;             pk.x = pack2(v.x, v.y);
;             pk.y = pack2(v.z, v.w);
;             *(uint2*)(xbb + (long)roff * 1024) = pk;
;           }
;           if (ssnb) {
;             float part = (v.x * v.x + v.y * v.y) + (v.z * v.z + v.w * v.w);
; #pragma unroll
;             for (int o = 32; o >= 1; o >>= 1) part += __shfl_xor(part, o);
;             if (ln == 0) ssnb[roff * 4] = part;
;           }
;         }
.LBB0_360:
.LBB0_361:
	v_add_co_u32_e32 v80, vcc, 0x30000, v136
	s_waitcnt lgkmcnt(0)
	s_nop 0
	v_addc_co_u32_e32 v81, vcc, 0, v137, vcc
	v_add_co_u32_e32 v82, vcc, 0x31000, v136
	s_nop 1
	v_addc_co_u32_e32 v83, vcc, 0, v137, vcc
	global_load_dwordx4 v[88:91], v[80:81], off
	s_nop 0
	global_load_dwordx4 v[80:83], v[82:83], off
	ds_read_b128 v[96:99], v128 offset:34816
	s_waitcnt vmcnt(5) lgkmcnt(0)
	v_pk_add_f32 v[92:93], v[92:93], v[96:97]
	v_add_co_u32_e32 v96, vcc, 0x22000, v134
	v_pk_add_f32 v[94:95], v[94:95], v[98:99]
	s_nop 0
	v_addc_co_u32_e32 v97, vcc, 0, v135, vcc
	s_and_b64 vcc, exec, s[8:9]
	global_store_dwordx4 v[96:97], v[92:95], off
	s_cbranch_vccnz .LBB0_363
	v_add_co_u32_e32 v98, vcc, 0x11000, v132
	v_cvt_pk_bf16_f32 v96, v92, v93
	v_cvt_pk_bf16_f32 v97, v94, v95
	v_addc_co_u32_e32 v99, vcc, 0, v133, vcc
	global_store_dwordx2 v[98:99], v[96:97], off
.LBB0_363:
	s_and_b64 vcc, exec, s[10:11]
	s_cbranch_vccnz .LBB0_367
	v_pk_mul_f32 v[92:93], v[92:93], v[92:93]
	v_pk_mul_f32 v[94:95], v[94:95], v[94:95]
	v_add_f32_e32 v92, v92, v93
	v_add_f32_e32 v94, v94, v95
	v_add_f32_e32 v92, v92, v94
	s_nop 1
	v_add_f32_dpp v92, v92, v92 quad_perm:[1,0,3,2] row_mask:0xf bank_mask:0xf
	s_nop 1
	v_add_f32_dpp v92, v92, v92 quad_perm:[2,3,0,1] row_mask:0xf bank_mask:0xf
	s_nop 1
	v_add_f32_dpp v92, v92, v92 row_half_mirror row_mask:0xf bank_mask:0xf
	s_nop 1
	v_add_f32_dpp v92, v92, v92 row_mirror row_mask:0xf bank_mask:0xf
	s_nop 1
	v_add_f32_dpp v92, v92, v92 row_bcast:15 row_mask:0xa bank_mask:0xf
	s_nop 1
	v_add_f32_dpp v92, v92, v92 row_bcast:31 row_mask:0xc bank_mask:0xf
	s_mov_b64 s[50:51], exec
	s_lshl_b64 exec, 1, 63
	global_store_dword v153, v92, s[56:57] offset:544
	s_mov_b64 exec, s[50:51]
.LBB0_366:
.LBB0_367:
	s_waitcnt lgkmcnt(0)
	ds_read_b128 v[92:95], v120 offset:35840
	s_waitcnt vmcnt(5) lgkmcnt(0)
	v_pk_add_f32 v[84:85], v[84:85], v[92:93]
	v_add_co_u32_e32 v92, vcc, 0x23000, v134
	v_pk_add_f32 v[86:87], v[86:87], v[94:95]
	s_nop 0
	v_addc_co_u32_e32 v93, vcc, 0, v135, vcc
	s_and_b64 vcc, exec, s[8:9]
	global_store_dwordx4 v[92:93], v[84:87], off
	s_cbranch_vccnz .LBB0_369
	v_add_co_u32_e32 v94, vcc, 0x11000, v132
	v_cvt_pk_bf16_f32 v92, v84, v85
	v_cvt_pk_bf16_f32 v93, v86, v87
	v_addc_co_u32_e32 v95, vcc, 0, v133, vcc
	global_store_dwordx2 v[94:95], v[92:93], off offset:2048
.LBB0_369:
	s_and_b64 vcc, exec, s[10:11]
	s_cbranch_vccnz .LBB0_373
	v_pk_mul_f32 v[84:85], v[84:85], v[84:85]
	v_pk_mul_f32 v[86:87], v[86:87], v[86:87]
	v_add_f32_e32 v84, v84, v85
	v_add_f32_e32 v86, v86, v87
	v_add_f32_e32 v84, v84, v86
	s_nop 1
	v_add_f32_dpp v84, v84, v84 quad_perm:[1,0,3,2] row_mask:0xf bank_mask:0xf
	s_nop 1
	v_add_f32_dpp v84, v84, v84 quad_perm:[2,3,0,1] row_mask:0xf bank_mask:0xf
	s_nop 1
	v_add_f32_dpp v84, v84, v84 row_half_mirror row_mask:0xf bank_mask:0xf
	s_nop 1
	v_add_f32_dpp v84, v84, v84 row_mirror row_mask:0xf bank_mask:0xf
	s_nop 1
	v_add_f32_dpp v84, v84, v84 row_bcast:15 row_mask:0xa bank_mask:0xf
	s_nop 1
	v_add_f32_dpp v84, v84, v84 row_bcast:31 row_mask:0xc bank_mask:0xf
	s_mov_b64 s[50:51], exec
	s_lshl_b64 exec, 1, 63
	global_store_dword v153, v84, s[56:57] offset:560
	s_mov_b64 exec, s[50:51]
.LBB0_372:
.LBB0_373:
	ds_write_b128 v112, v[64:67]
	ds_write_b128 v113, v[68:71]
	ds_write_b128 v114, v[72:75]
	ds_write_b128 v115, v[76:79]
	v_add_co_u32_e32 v64, vcc, 0x32000, v136
	s_waitcnt lgkmcnt(0)
	s_barrier
	s_nop 0
	v_addc_co_u32_e32 v65, vcc, 0, v137, vcc
	v_add_co_u32_e32 v66, vcc, 0x33000, v136
	s_nop 1
	v_addc_co_u32_e32 v67, vcc, 0, v137, vcc
	global_load_dwordx4 v[76:79], v[64:65], off
	global_load_dwordx4 v[68:71], v[66:67], off
	ds_read_b128 v[64:67], v121
	v_add_co_u32_e32 v72, vcc, 0x30000, v134
	s_waitcnt vmcnt(5) lgkmcnt(0)
	v_pk_add_f32 v[64:65], v[88:89], v[64:65]
	v_addc_co_u32_e32 v73, vcc, 0, v135, vcc
	v_pk_add_f32 v[66:67], v[90:91], v[66:67]
	s_and_b64 vcc, exec, s[8:9]
	global_store_dwordx4 v[72:73], v[64:67], off
	s_cbranch_vccnz .LBB0_375
	v_add_co_u32_e32 v74, vcc, 0x18000, v132
	v_cvt_pk_bf16_f32 v72, v64, v65
	v_cvt_pk_bf16_f32 v73, v66, v67
	v_addc_co_u32_e32 v75, vcc, 0, v133, vcc
	global_store_dwordx2 v[74:75], v[72:73], off
.LBB0_375:
	s_and_b64 vcc, exec, s[10:11]
	s_cbranch_vccnz .LBB0_379
	v_pk_mul_f32 v[64:65], v[64:65], v[64:65]
	v_pk_mul_f32 v[66:67], v[66:67], v[66:67]
	v_add_f32_e32 v64, v64, v65
	v_add_f32_e32 v66, v66, v67
	v_add_f32_e32 v64, v64, v66
	s_nop 1
	v_add_f32_dpp v64, v64, v64 quad_perm:[1,0,3,2] row_mask:0xf bank_mask:0xf
	s_nop 1
	v_add_f32_dpp v64, v64, v64 quad_perm:[2,3,0,1] row_mask:0xf bank_mask:0xf
	s_nop 1
	v_add_f32_dpp v64, v64, v64 row_half_mirror row_mask:0xf bank_mask:0xf
	s_nop 1
	v_add_f32_dpp v64, v64, v64 row_mirror row_mask:0xf bank_mask:0xf
	s_nop 1
	v_add_f32_dpp v64, v64, v64 row_bcast:15 row_mask:0xa bank_mask:0xf
	s_nop 1
	v_add_f32_dpp v64, v64, v64 row_bcast:31 row_mask:0xc bank_mask:0xf
	s_mov_b64 s[50:51], exec
	s_lshl_b64 exec, 1, 63
	global_store_dword v153, v64, s[56:57] offset:768
	s_mov_b64 exec, s[50:51]
.LBB0_378:
.LBB0_379:
	s_waitcnt lgkmcnt(0)
	ds_read_b128 v[64:67], v122
	v_add_co_u32_e32 v72, vcc, 0x31000, v134
	s_waitcnt vmcnt(5) lgkmcnt(0)
	v_pk_add_f32 v[64:65], v[80:81], v[64:65]
	v_addc_co_u32_e32 v73, vcc, 0, v135, vcc
	v_pk_add_f32 v[66:67], v[82:83], v[66:67]
	s_and_b64 vcc, exec, s[8:9]
	global_store_dwordx4 v[72:73], v[64:67], off
	s_cbranch_vccnz .LBB0_381
	v_add_co_u32_e32 v74, vcc, 0x18000, v132
	v_cvt_pk_bf16_f32 v72, v64, v65
	v_cvt_pk_bf16_f32 v73, v66, v67
	v_addc_co_u32_e32 v75, vcc, 0, v133, vcc
	global_store_dwordx2 v[74:75], v[72:73], off offset:2048
;   __device__ __forceinline__ bf16* z() const { return (bf16*)(ws + OFF_z); }
; __device__ __forceinline__ void gemm_phase(const GemmArgs& a, char* smem) {
;     ...
; #pragma unroll
;         for (int r = 0; r < 2; ++r) {
;           const int k = 2 * hf + r;
;           const int roff = ai * 128 + m * 16 + k;
;           const f32x4 av = *(const f32x4*)(reg + ((lrd + k * 1024) ^ (k << 4)));
;           float4 v = xv[un & 1][r];
;           v.x += av[0]; v.y += av[1]; v.z += av[2]; v.w += av[3];
;           *(float4*)(xoutb + (long)roff * 1024) = v;
;           if (xbb) {
;             uint2 pk;
;             pk.x = pack2(v.x, v.y);
;             pk.y = pack2(v.z, v.w);
;             *(uint2*)(xbb + (long)roff * 1024) = pk;
;           }
;           if (ssnb) {
;             float part = (v.x * v.x + v.y * v.y) + (v.z * v.z + v.w * v.w);
; #pragma unroll
;             for (int o = 32; o >= 1; o >>= 1) part += __shfl_xor(part, o);
;             if (ln == 0) ssnb[roff * 4] = part;
;           }
;         }
.LBB0_381:
	s_and_b64 vcc, exec, s[10:11]
	s_cbranch_vccnz .LBB0_385
	v_pk_mul_f32 v[64:65], v[64:65], v[64:65]
	v_pk_mul_f32 v[66:67], v[66:67], v[66:67]
	v_add_f32_e32 v64, v64, v65
	v_add_f32_e32 v66, v66, v67
	v_add_f32_e32 v64, v64, v66
	s_nop 1
	v_add_f32_dpp v64, v64, v64 quad_perm:[1,0,3,2] row_mask:0xf bank_mask:0xf
	s_nop 1
	v_add_f32_dpp v64, v64, v64 quad_perm:[2,3,0,1] row_mask:0xf bank_mask:0xf
	s_nop 1
	v_add_f32_dpp v64, v64, v64 row_half_mirror row_mask:0xf bank_mask:0xf
	s_nop 1
	v_add_f32_dpp v64, v64, v64 row_mirror row_mask:0xf bank_mask:0xf
	s_nop 1
	v_add_f32_dpp v64, v64, v64 row_bcast:15 row_mask:0xa bank_mask:0xf
	s_nop 1
	v_add_f32_dpp v64, v64, v64 row_bcast:31 row_mask:0xc bank_mask:0xf
	s_mov_b64 s[50:51], exec
	s_lshl_b64 exec, 1, 63
	global_store_dword v153, v64, s[56:57] offset:784
	s_mov_b64 exec, s[50:51]
.LBB0_384:
.LBB0_385:
	v_add_co_u32_e32 v64, vcc, 0x80000, v136
	s_waitcnt lgkmcnt(0)
	s_nop 0
	v_addc_co_u32_e32 v65, vcc, 0, v137, vcc
	v_add_co_u32_e32 v66, vcc, 0x81000, v136
	s_nop 1
	v_addc_co_u32_e32 v67, vcc, 0, v137, vcc
	global_load_dwordx4 v[72:75], v[64:65], off
	s_nop 0
	global_load_dwordx4 v[64:67], v[66:67], off
	ds_read_b128 v[80:83], v116
	s_waitcnt vmcnt(5) lgkmcnt(0)
	v_pk_add_f32 v[76:77], v[76:77], v[80:81]
	v_add_co_u32_e32 v80, vcc, 0x32000, v134
	v_pk_add_f32 v[78:79], v[78:79], v[82:83]
	s_nop 0
	v_addc_co_u32_e32 v81, vcc, 0, v135, vcc
	s_and_b64 vcc, exec, s[8:9]
	global_store_dwordx4 v[80:81], v[76:79], off
	s_cbranch_vccnz .LBB0_387
	v_add_co_u32_e32 v82, vcc, 0x19000, v132
	v_cvt_pk_bf16_f32 v80, v76, v77
	v_cvt_pk_bf16_f32 v81, v78, v79
	v_addc_co_u32_e32 v83, vcc, 0, v133, vcc
	global_store_dwordx2 v[82:83], v[80:81], off
.LBB0_387:
	s_and_b64 vcc, exec, s[10:11]
	s_cbranch_vccnz .LBB0_391
	v_pk_mul_f32 v[76:77], v[76:77], v[76:77]
	v_pk_mul_f32 v[78:79], v[78:79], v[78:79]
	v_add_f32_e32 v76, v76, v77
	v_add_f32_e32 v78, v78, v79
	v_add_f32_e32 v76, v76, v78
	s_nop 1
	v_add_f32_dpp v76, v76, v76 quad_perm:[1,0,3,2] row_mask:0xf bank_mask:0xf
	s_nop 1
	v_add_f32_dpp v76, v76, v76 quad_perm:[2,3,0,1] row_mask:0xf bank_mask:0xf
	s_nop 1
	v_add_f32_dpp v76, v76, v76 row_half_mirror row_mask:0xf bank_mask:0xf
	s_nop 1
	v_add_f32_dpp v76, v76, v76 row_mirror row_mask:0xf bank_mask:0xf
	s_nop 1
	v_add_f32_dpp v76, v76, v76 row_bcast:15 row_mask:0xa bank_mask:0xf
	s_nop 1
	v_add_f32_dpp v76, v76, v76 row_bcast:31 row_mask:0xc bank_mask:0xf
	s_mov_b64 s[50:51], exec
	s_lshl_b64 exec, 1, 63
	global_store_dword v153, v76, s[56:57] offset:800
	s_mov_b64 exec, s[50:51]
.LBB0_390:
.LBB0_391:
	s_waitcnt lgkmcnt(0)
	ds_read_b128 v[76:79], v108
	s_waitcnt vmcnt(5) lgkmcnt(0)
	v_pk_add_f32 v[68:69], v[68:69], v[76:77]
	v_add_co_u32_e32 v76, vcc, 0x33000, v134
	v_pk_add_f32 v[70:71], v[70:71], v[78:79]
	s_nop 0
	v_addc_co_u32_e32 v77, vcc, 0, v135, vcc
	s_and_b64 vcc, exec, s[8:9]
	global_store_dwordx4 v[76:77], v[68:71], off
	s_cbranch_vccnz .LBB0_393
	v_add_co_u32_e32 v78, vcc, 0x19000, v132
	v_cvt_pk_bf16_f32 v76, v68, v69
	v_cvt_pk_bf16_f32 v77, v70, v71
	v_addc_co_u32_e32 v79, vcc, 0, v133, vcc
	global_store_dwordx2 v[78:79], v[76:77], off offset:2048
.LBB0_393:
	s_and_b64 vcc, exec, s[10:11]
	s_cbranch_vccnz .LBB0_397
	v_pk_mul_f32 v[68:69], v[68:69], v[68:69]
	v_pk_mul_f32 v[70:71], v[70:71], v[70:71]
	v_add_f32_e32 v68, v68, v69
	v_add_f32_e32 v70, v70, v71
	v_add_f32_e32 v68, v68, v70
	s_nop 1
	v_add_f32_dpp v68, v68, v68 quad_perm:[1,0,3,2] row_mask:0xf bank_mask:0xf
	s_nop 1
	v_add_f32_dpp v68, v68, v68 quad_perm:[2,3,0,1] row_mask:0xf bank_mask:0xf
	s_nop 1
	v_add_f32_dpp v68, v68, v68 row_half_mirror row_mask:0xf bank_mask:0xf
	s_nop 1
	v_add_f32_dpp v68, v68, v68 row_mirror row_mask:0xf bank_mask:0xf
	s_nop 1
	v_add_f32_dpp v68, v68, v68 row_bcast:15 row_mask:0xa bank_mask:0xf
	s_nop 1
	v_add_f32_dpp v68, v68, v68 row_bcast:31 row_mask:0xc bank_mask:0xf
	s_mov_b64 s[50:51], exec
	s_lshl_b64 exec, 1, 63
	global_store_dword v153, v68, s[56:57] offset:816
	s_mov_b64 exec, s[50:51]
.LBB0_396:
.LBB0_397:
	ds_write_b128 v100, v[48:51] offset:32768
	ds_write_b128 v101, v[52:55] offset:32768
	ds_write_b128 v102, v[56:59] offset:32768
	ds_write_b128 v103, v[60:63] offset:32768
	v_add_co_u32_e32 v48, vcc, 0x82000, v136
	s_waitcnt lgkmcnt(0)
	s_barrier
	s_nop 0
	v_addc_co_u32_e32 v49, vcc, 0, v137, vcc
	v_add_co_u32_e32 v50, vcc, 0x83000, v136
	s_nop 1
	v_addc_co_u32_e32 v51, vcc, 0, v137, vcc
	global_load_dwordx4 v[60:63], v[48:49], off
	global_load_dwordx4 v[52:55], v[50:51], off
	ds_read_b128 v[48:51], v138 offset:32768
	v_add_co_u32_e32 v56, vcc, 0x80000, v134
	s_waitcnt vmcnt(5) lgkmcnt(0)
	v_pk_add_f32 v[48:49], v[72:73], v[48:49]
	v_addc_co_u32_e32 v57, vcc, 0, v135, vcc
	v_pk_add_f32 v[50:51], v[74:75], v[50:51]
	s_and_b64 vcc, exec, s[8:9]
	global_store_dwordx4 v[56:57], v[48:51], off
	s_cbranch_vccnz .LBB0_399
	v_add_co_u32_e32 v58, vcc, 0x40000, v132
	v_cvt_pk_bf16_f32 v56, v48, v49
	v_cvt_pk_bf16_f32 v57, v50, v51
	v_addc_co_u32_e32 v59, vcc, 0, v133, vcc
	global_store_dwordx2 v[58:59], v[56:57], off
.LBB0_399:
	s_and_b64 vcc, exec, s[10:11]
	s_cbranch_vccnz .LBB0_403
	v_pk_mul_f32 v[48:49], v[48:49], v[48:49]
	v_pk_mul_f32 v[50:51], v[50:51], v[50:51]
	v_add_f32_e32 v48, v48, v49
	v_add_f32_e32 v50, v50, v51
	v_add_f32_e32 v48, v48, v50
	s_nop 1
	v_add_f32_dpp v48, v48, v48 quad_perm:[1,0,3,2] row_mask:0xf bank_mask:0xf
	s_nop 1
	v_add_f32_dpp v48, v48, v48 quad_perm:[2,3,0,1] row_mask:0xf bank_mask:0xf
	s_nop 1
	v_add_f32_dpp v48, v48, v48 row_half_mirror row_mask:0xf bank_mask:0xf
	s_nop 1
	v_add_f32_dpp v48, v48, v48 row_mirror row_mask:0xf bank_mask:0xf
	s_nop 1
	v_add_f32_dpp v48, v48, v48 row_bcast:15 row_mask:0xa bank_mask:0xf
	s_nop 1
	v_add_f32_dpp v48, v48, v48 row_bcast:31 row_mask:0xc bank_mask:0xf
	s_mov_b64 s[50:51], exec
	s_lshl_b64 exec, 1, 63
	global_store_dword v153, v48, s[56:57] offset:2048
	s_mov_b64 exec, s[50:51]
;   __device__ __forceinline__ bf16* z() const { return (bf16*)(ws + OFF_z); }
; __device__ __forceinline__ void gemm_phase(const GemmArgs& a, char* smem) {
;     ...
; #pragma unroll
;         for (int r = 0; r < 2; ++r) {
;           const int k = 2 * hf + r;
;           const int roff = ai * 128 + m * 16 + k;
;           const f32x4 av = *(const f32x4*)(reg + ((lrd + k * 1024) ^ (k << 4)));
;           float4 v = xv[un & 1][r];
;           v.x += av[0]; v.y += av[1]; v.z += av[2]; v.w += av[3];
;           *(float4*)(xoutb + (long)roff * 1024) = v;
;           if (xbb) {
;             uint2 pk;
;             pk.x = pack2(v.x, v.y);
;             pk.y = pack2(v.z, v.w);
;             *(uint2*)(xbb + (long)roff * 1024) = pk;
;           }
;           if (ssnb) {
;             float part = (v.x * v.x + v.y * v.y) + (v.z * v.z + v.w * v.w);
; #pragma unroll
;             for (int o = 32; o >= 1; o >>= 1) part += __shfl_xor(part, o);
;             if (ln == 0) ssnb[roff * 4] = part;
;           }
;         }
.LBB0_402:
.LBB0_403:
	s_waitcnt lgkmcnt(0)
	ds_read_b128 v[48:51], v139 offset:33792
	v_add_co_u32_e32 v56, vcc, 0x81000, v134
	s_waitcnt vmcnt(5) lgkmcnt(0)
	v_pk_add_f32 v[48:49], v[64:65], v[48:49]
	v_addc_co_u32_e32 v57, vcc, 0, v135, vcc
	v_pk_add_f32 v[50:51], v[66:67], v[50:51]
	s_and_b64 vcc, exec, s[8:9]
	global_store_dwordx4 v[56:57], v[48:51], off
	s_cbranch_vccnz .LBB0_405
	v_add_co_u32_e32 v58, vcc, 0x40000, v132
	v_cvt_pk_bf16_f32 v56, v48, v49
	v_cvt_pk_bf16_f32 v57, v50, v51
	v_addc_co_u32_e32 v59, vcc, 0, v133, vcc
	global_store_dwordx2 v[58:59], v[56:57], off offset:2048
.LBB0_405:
	s_and_b64 vcc, exec, s[10:11]
	s_cbranch_vccnz .LBB0_409
	v_pk_mul_f32 v[48:49], v[48:49], v[48:49]
	v_pk_mul_f32 v[50:51], v[50:51], v[50:51]
	v_add_f32_e32 v48, v48, v49
	v_add_f32_e32 v50, v50, v51
	v_add_f32_e32 v48, v48, v50
	s_nop 1
	v_add_f32_dpp v48, v48, v48 quad_perm:[1,0,3,2] row_mask:0xf bank_mask:0xf
	s_nop 1
	v_add_f32_dpp v48, v48, v48 quad_perm:[2,3,0,1] row_mask:0xf bank_mask:0xf
	s_nop 1
	v_add_f32_dpp v48, v48, v48 row_half_mirror row_mask:0xf bank_mask:0xf
	s_nop 1
	v_add_f32_dpp v48, v48, v48 row_mirror row_mask:0xf bank_mask:0xf
	s_nop 1
	v_add_f32_dpp v48, v48, v48 row_bcast:15 row_mask:0xa bank_mask:0xf
	s_nop 1
	v_add_f32_dpp v48, v48, v48 row_bcast:31 row_mask:0xc bank_mask:0xf
	s_mov_b64 s[50:51], exec
	s_lshl_b64 exec, 1, 63
	global_store_dword v153, v48, s[56:57] offset:2064
	s_mov_b64 exec, s[50:51]
.LBB0_408:
.LBB0_409:
	v_add_co_u32_e32 v48, vcc, 0x90000, v136
	s_waitcnt lgkmcnt(0)
	s_nop 0
	v_addc_co_u32_e32 v49, vcc, 0, v137, vcc
	v_add_co_u32_e32 v50, vcc, 0x91000, v136
	s_nop 1
	v_addc_co_u32_e32 v51, vcc, 0, v137, vcc
	global_load_dwordx4 v[56:59], v[48:49], off
	s_nop 0
	global_load_dwordx4 v[48:51], v[50:51], off
	ds_read_b128 v[64:67], v128 offset:34816
	s_waitcnt vmcnt(5) lgkmcnt(0)
	v_pk_add_f32 v[60:61], v[60:61], v[64:65]
	v_add_co_u32_e32 v64, vcc, 0x82000, v134
	v_pk_add_f32 v[62:63], v[62:63], v[66:67]
	s_nop 0
	v_addc_co_u32_e32 v65, vcc, 0, v135, vcc
	s_and_b64 vcc, exec, s[8:9]
	global_store_dwordx4 v[64:65], v[60:63], off
	s_cbranch_vccnz .LBB0_411
	v_add_co_u32_e32 v66, vcc, 0x41000, v132
	v_cvt_pk_bf16_f32 v64, v60, v61
	v_cvt_pk_bf16_f32 v65, v62, v63
	v_addc_co_u32_e32 v67, vcc, 0, v133, vcc
	global_store_dwordx2 v[66:67], v[64:65], off
.LBB0_411:
	s_and_b64 vcc, exec, s[10:11]
	s_cbranch_vccnz .LBB0_415
	v_pk_mul_f32 v[60:61], v[60:61], v[60:61]
	v_pk_mul_f32 v[62:63], v[62:63], v[62:63]
	v_add_f32_e32 v60, v60, v61
	v_add_f32_e32 v62, v62, v63
	v_add_f32_e32 v60, v60, v62
	s_nop 1
	v_add_f32_dpp v60, v60, v60 quad_perm:[1,0,3,2] row_mask:0xf bank_mask:0xf
	s_nop 1
	v_add_f32_dpp v60, v60, v60 quad_perm:[2,3,0,1] row_mask:0xf bank_mask:0xf
	s_nop 1
	v_add_f32_dpp v60, v60, v60 row_half_mirror row_mask:0xf bank_mask:0xf
	s_nop 1
	v_add_f32_dpp v60, v60, v60 row_mirror row_mask:0xf bank_mask:0xf
	s_nop 1
	v_add_f32_dpp v60, v60, v60 row_bcast:15 row_mask:0xa bank_mask:0xf
	s_nop 1
	v_add_f32_dpp v60, v60, v60 row_bcast:31 row_mask:0xc bank_mask:0xf
	s_mov_b64 s[50:51], exec
	s_lshl_b64 exec, 1, 63
	global_store_dword v153, v60, s[56:57] offset:2080
	s_mov_b64 exec, s[50:51]
.LBB0_414:
.LBB0_415:
	s_waitcnt lgkmcnt(0)
	ds_read_b128 v[60:63], v120 offset:35840
	s_waitcnt vmcnt(5) lgkmcnt(0)
	v_pk_add_f32 v[52:53], v[52:53], v[60:61]
	v_add_co_u32_e32 v60, vcc, 0x83000, v134
	v_pk_add_f32 v[54:55], v[54:55], v[62:63]
	s_nop 0
	v_addc_co_u32_e32 v61, vcc, 0, v135, vcc
	s_and_b64 vcc, exec, s[8:9]
	global_store_dwordx4 v[60:61], v[52:55], off
	s_cbranch_vccnz .LBB0_417
	v_add_co_u32_e32 v62, vcc, 0x41000, v132
	v_cvt_pk_bf16_f32 v60, v52, v53
	v_cvt_pk_bf16_f32 v61, v54, v55
	v_addc_co_u32_e32 v63, vcc, 0, v133, vcc
	global_store_dwordx2 v[62:63], v[60:61], off offset:2048
.LBB0_417:
	s_and_b64 vcc, exec, s[10:11]
	s_cbranch_vccnz .LBB0_421
	v_pk_mul_f32 v[52:53], v[52:53], v[52:53]
	v_pk_mul_f32 v[54:55], v[54:55], v[54:55]
	v_add_f32_e32 v52, v52, v53
	v_add_f32_e32 v54, v54, v55
	v_add_f32_e32 v52, v52, v54
	s_nop 1
	v_add_f32_dpp v52, v52, v52 quad_perm:[1,0,3,2] row_mask:0xf bank_mask:0xf
	s_nop 1
	v_add_f32_dpp v52, v52, v52 quad_perm:[2,3,0,1] row_mask:0xf bank_mask:0xf
	s_nop 1
	v_add_f32_dpp v52, v52, v52 row_half_mirror row_mask:0xf bank_mask:0xf
	s_nop 1
	v_add_f32_dpp v52, v52, v52 row_mirror row_mask:0xf bank_mask:0xf
	s_nop 1
	v_add_f32_dpp v52, v52, v52 row_bcast:15 row_mask:0xa bank_mask:0xf
	s_nop 1
	v_add_f32_dpp v52, v52, v52 row_bcast:31 row_mask:0xc bank_mask:0xf
	s_mov_b64 s[50:51], exec
	s_lshl_b64 exec, 1, 63
	global_store_dword v153, v52, s[56:57] offset:2096
	s_mov_b64 exec, s[50:51]
.LBB0_420:
.LBB0_421:
	ds_write_b128 v112, v[32:35]
	ds_write_b128 v113, v[36:39]
	ds_write_b128 v114, v[40:43]
	ds_write_b128 v115, v[44:47]
	v_add_co_u32_e32 v32, vcc, 0x92000, v136
	s_waitcnt lgkmcnt(0)
	s_barrier
	s_nop 0
	v_addc_co_u32_e32 v33, vcc, 0, v137, vcc
	v_add_co_u32_e32 v34, vcc, 0x93000, v136
	s_nop 1
	v_addc_co_u32_e32 v35, vcc, 0, v137, vcc
	global_load_dwordx4 v[44:47], v[32:33], off
	global_load_dwordx4 v[36:39], v[34:35], off
	ds_read_b128 v[32:35], v121
	v_add_co_u32_e32 v40, vcc, 0x90000, v134
	s_waitcnt vmcnt(5) lgkmcnt(0)
	v_pk_add_f32 v[32:33], v[56:57], v[32:33]
	v_addc_co_u32_e32 v41, vcc, 0, v135, vcc
	v_pk_add_f32 v[34:35], v[58:59], v[34:35]
	s_and_b64 vcc, exec, s[8:9]
	global_store_dwordx4 v[40:41], v[32:35], off
	s_cbranch_vccnz .LBB0_423
	v_add_co_u32_e32 v42, vcc, 0x48000, v132
	v_cvt_pk_bf16_f32 v40, v32, v33
	v_cvt_pk_bf16_f32 v41, v34, v35
	v_addc_co_u32_e32 v43, vcc, 0, v133, vcc
	global_store_dwordx2 v[42:43], v[40:41], off
;   __device__ __forceinline__ bf16* z() const { return (bf16*)(ws + OFF_z); }
; #define BAR() __builtin_amdgcn_s_barrier()
; #define WAIT_L(n) asm volatile("s_waitcnt lgkmcnt(" #n ")" ::: "memory")
; __device__ __forceinline__ void gemm_phase(const GemmArgs& a, char* smem) {
;     ...
;       float4 xv[2][2];
;       xv[0][0] = *(const float4*)(xinb);
;       xv[0][1] = *(const float4*)(xinb + 1024);
; #pragma unroll
;       for (int un = 0; un < 16; ++un) {
;         const int ps = un >> 1, hf = un & 1;
;         const int ai = ps >> 2, m = ps & 3;
;         char* reg = smem + ((ps & 1) ? 6 * HT_B : 2 * HT_B);
;         if (hf == 0) {
; #pragma unroll
;           for (int bj = 0; bj < 2; ++bj)
; #pragma unroll
;             for (int n = 0; n < 2; ++n) {
;               const int c4 = bj * 32 + wc * 8 + n * 4 + fq;
;               *(f32x4*)(reg + lwr + ((c4 ^ fr) << 4)) = acc[ai][bj][m][n];
;             }
;           WAIT_L(0);
;           BAR();
;         }
;         if (un + 1 < 16) {
;           const int ps2 = (un + 1) >> 1, hf2 = (un + 1) & 1;
;           const int off2 = ((ps2 >> 2) * 128 + (ps2 & 3) * 16 + 2 * hf2) * 1024;
;           xv[(un + 1) & 1][0] = *(const float4*)(xinb + off2);
;           xv[(un + 1) & 1][1] = *(const float4*)(xinb + off2 + 1024);
;         }
; #pragma unroll
;         for (int r = 0; r < 2; ++r) {
;           const int k = 2 * hf + r;
;           const int roff = ai * 128 + m * 16 + k;
;           const f32x4 av = *(const f32x4*)(reg + ((lrd + k * 1024) ^ (k << 4)));
;           float4 v = xv[un & 1][r];
;           v.x += av[0]; v.y += av[1]; v.z += av[2]; v.w += av[3];
;           *(float4*)(xoutb + (long)roff * 1024) = v;
;           if (xbb) {
;             uint2 pk;
;             pk.x = pack2(v.x, v.y);
;             pk.y = pack2(v.z, v.w);
;             *(uint2*)(xbb + (long)roff * 1024) = pk;
;           }
;           if (ssnb) {
;             float part = (v.x * v.x + v.y * v.y) + (v.z * v.z + v.w * v.w);
; #pragma unroll
;             for (int o = 32; o >= 1; o >>= 1) part += __shfl_xor(part, o);
;             if (ln == 0) ssnb[roff * 4] = part;
;           }
;         }
;       }
.LBB0_423:
	s_and_b64 vcc, exec, s[10:11]
	s_cbranch_vccnz .LBB0_427
	v_pk_mul_f32 v[32:33], v[32:33], v[32:33]
	v_pk_mul_f32 v[34:35], v[34:35], v[34:35]
	v_add_f32_e32 v32, v32, v33
	v_add_f32_e32 v34, v34, v35
	v_add_f32_e32 v32, v32, v34
	s_nop 1
	v_add_f32_dpp v32, v32, v32 quad_perm:[1,0,3,2] row_mask:0xf bank_mask:0xf
	s_nop 1
	v_add_f32_dpp v32, v32, v32 quad_perm:[2,3,0,1] row_mask:0xf bank_mask:0xf
	s_nop 1
	v_add_f32_dpp v32, v32, v32 row_half_mirror row_mask:0xf bank_mask:0xf
	s_nop 1
	v_add_f32_dpp v32, v32, v32 row_mirror row_mask:0xf bank_mask:0xf
	s_nop 1
	v_add_f32_dpp v32, v32, v32 row_bcast:15 row_mask:0xa bank_mask:0xf
	s_nop 1
	v_add_f32_dpp v32, v32, v32 row_bcast:31 row_mask:0xc bank_mask:0xf
	s_mov_b64 s[50:51], exec
	s_lshl_b64 exec, 1, 63
	global_store_dword v153, v32, s[56:57] offset:2304
	s_mov_b64 exec, s[50:51]
.LBB0_426:
.LBB0_427:
	s_waitcnt lgkmcnt(0)
	ds_read_b128 v[32:35], v122
	v_add_co_u32_e32 v40, vcc, 0x91000, v134
	s_waitcnt vmcnt(5) lgkmcnt(0)
	v_pk_add_f32 v[32:33], v[48:49], v[32:33]
	v_addc_co_u32_e32 v41, vcc, 0, v135, vcc
	v_pk_add_f32 v[34:35], v[50:51], v[34:35]
	s_and_b64 vcc, exec, s[8:9]
	global_store_dwordx4 v[40:41], v[32:35], off
	s_cbranch_vccnz .LBB0_429
	v_add_co_u32_e32 v42, vcc, 0x48000, v132
	v_cvt_pk_bf16_f32 v40, v32, v33
	v_cvt_pk_bf16_f32 v41, v34, v35
	v_addc_co_u32_e32 v43, vcc, 0, v133, vcc
	global_store_dwordx2 v[42:43], v[40:41], off offset:2048
.LBB0_429:
	s_and_b64 vcc, exec, s[10:11]
	s_cbranch_vccnz .LBB0_433
	v_pk_mul_f32 v[32:33], v[32:33], v[32:33]
	v_pk_mul_f32 v[34:35], v[34:35], v[34:35]
	v_add_f32_e32 v32, v32, v33
	v_add_f32_e32 v34, v34, v35
	v_add_f32_e32 v32, v32, v34
	s_nop 1
	v_add_f32_dpp v32, v32, v32 quad_perm:[1,0,3,2] row_mask:0xf bank_mask:0xf
	s_nop 1
	v_add_f32_dpp v32, v32, v32 quad_perm:[2,3,0,1] row_mask:0xf bank_mask:0xf
	s_nop 1
	v_add_f32_dpp v32, v32, v32 row_half_mirror row_mask:0xf bank_mask:0xf
	s_nop 1
	v_add_f32_dpp v32, v32, v32 row_mirror row_mask:0xf bank_mask:0xf
	s_nop 1
	v_add_f32_dpp v32, v32, v32 row_bcast:15 row_mask:0xa bank_mask:0xf
	s_nop 1
	v_add_f32_dpp v32, v32, v32 row_bcast:31 row_mask:0xc bank_mask:0xf
	s_mov_b64 s[50:51], exec
	s_lshl_b64 exec, 1, 63
	global_store_dword v153, v32, s[56:57] offset:2320
	s_mov_b64 exec, s[50:51]
.LBB0_432:
.LBB0_433:
	v_add_co_u32_e32 v32, vcc, 0xa0000, v136
	s_waitcnt lgkmcnt(0)
	s_nop 0
	v_addc_co_u32_e32 v33, vcc, 0, v137, vcc
	v_add_co_u32_e32 v34, vcc, 0xa1000, v136
	s_nop 1
	v_addc_co_u32_e32 v35, vcc, 0, v137, vcc
	global_load_dwordx4 v[40:43], v[32:33], off
	s_nop 0
	global_load_dwordx4 v[32:35], v[34:35], off
	ds_read_b128 v[48:51], v116
	s_waitcnt vmcnt(5) lgkmcnt(0)
	v_pk_add_f32 v[44:45], v[44:45], v[48:49]
	v_add_co_u32_e32 v48, vcc, 0x92000, v134
	v_pk_add_f32 v[46:47], v[46:47], v[50:51]
	s_nop 0
	v_addc_co_u32_e32 v49, vcc, 0, v135, vcc
	s_and_b64 vcc, exec, s[8:9]
	global_store_dwordx4 v[48:49], v[44:47], off
	s_cbranch_vccnz .LBB0_435
	v_add_co_u32_e32 v50, vcc, 0x49000, v132
	v_cvt_pk_bf16_f32 v48, v44, v45
	v_cvt_pk_bf16_f32 v49, v46, v47
	v_addc_co_u32_e32 v51, vcc, 0, v133, vcc
	global_store_dwordx2 v[50:51], v[48:49], off
.LBB0_435:
	s_and_b64 vcc, exec, s[10:11]
	s_cbranch_vccnz .LBB0_439
	v_pk_mul_f32 v[44:45], v[44:45], v[44:45]
	v_pk_mul_f32 v[46:47], v[46:47], v[46:47]
	v_add_f32_e32 v44, v44, v45
	v_add_f32_e32 v46, v46, v47
	v_add_f32_e32 v44, v44, v46
	s_nop 1
	v_add_f32_dpp v44, v44, v44 quad_perm:[1,0,3,2] row_mask:0xf bank_mask:0xf
	s_nop 1
	v_add_f32_dpp v44, v44, v44 quad_perm:[2,3,0,1] row_mask:0xf bank_mask:0xf
	s_nop 1
	v_add_f32_dpp v44, v44, v44 row_half_mirror row_mask:0xf bank_mask:0xf
	s_nop 1
	v_add_f32_dpp v44, v44, v44 row_mirror row_mask:0xf bank_mask:0xf
	s_nop 1
	v_add_f32_dpp v44, v44, v44 row_bcast:15 row_mask:0xa bank_mask:0xf
	s_nop 1
	v_add_f32_dpp v44, v44, v44 row_bcast:31 row_mask:0xc bank_mask:0xf
	s_mov_b64 s[50:51], exec
	s_lshl_b64 exec, 1, 63
	global_store_dword v153, v44, s[56:57] offset:2336
	s_mov_b64 exec, s[50:51]
.LBB0_438:
.LBB0_439:
	s_waitcnt lgkmcnt(0)
	ds_read_b128 v[44:47], v108
	s_waitcnt vmcnt(5) lgkmcnt(0)
	v_pk_add_f32 v[36:37], v[36:37], v[44:45]
	v_add_co_u32_e32 v44, vcc, 0x93000, v134
	v_pk_add_f32 v[38:39], v[38:39], v[46:47]
	s_nop 0
	v_addc_co_u32_e32 v45, vcc, 0, v135, vcc
	s_and_b64 vcc, exec, s[8:9]
	global_store_dwordx4 v[44:45], v[36:39], off
	s_cbranch_vccnz .LBB0_441
	v_add_co_u32_e32 v46, vcc, 0x49000, v132
	v_cvt_pk_bf16_f32 v44, v36, v37
	v_cvt_pk_bf16_f32 v45, v38, v39
	v_addc_co_u32_e32 v47, vcc, 0, v133, vcc
	global_store_dwordx2 v[46:47], v[44:45], off offset:2048
.LBB0_441:
	s_and_b64 vcc, exec, s[10:11]
	s_cbranch_vccnz .LBB0_445
	v_pk_mul_f32 v[36:37], v[36:37], v[36:37]
	v_pk_mul_f32 v[38:39], v[38:39], v[38:39]
	v_add_f32_e32 v36, v36, v37
	v_add_f32_e32 v38, v38, v39
	v_add_f32_e32 v36, v36, v38
	s_nop 1
	v_add_f32_dpp v36, v36, v36 quad_perm:[1,0,3,2] row_mask:0xf bank_mask:0xf
	s_nop 1
	v_add_f32_dpp v36, v36, v36 quad_perm:[2,3,0,1] row_mask:0xf bank_mask:0xf
	s_nop 1
	v_add_f32_dpp v36, v36, v36 row_half_mirror row_mask:0xf bank_mask:0xf
	s_nop 1
	v_add_f32_dpp v36, v36, v36 row_mirror row_mask:0xf bank_mask:0xf
	s_nop 1
	v_add_f32_dpp v36, v36, v36 row_bcast:15 row_mask:0xa bank_mask:0xf
	s_nop 1
	v_add_f32_dpp v36, v36, v36 row_bcast:31 row_mask:0xc bank_mask:0xf
	s_mov_b64 s[50:51], exec
	s_lshl_b64 exec, 1, 63
	global_store_dword v153, v36, s[56:57] offset:2352
	s_mov_b64 exec, s[50:51]
;   __device__ __forceinline__ bf16* z() const { return (bf16*)(ws + OFF_z); }
; #define BAR() __builtin_amdgcn_s_barrier()
; #define WAIT_L(n) asm volatile("s_waitcnt lgkmcnt(" #n ")" ::: "memory")
; __device__ __forceinline__ void gemm_phase(const GemmArgs& a, char* smem) {
;     ...
;       float4 xv[2][2];
;       xv[0][0] = *(const float4*)(xinb);
;       xv[0][1] = *(const float4*)(xinb + 1024);
; #pragma unroll
;       for (int un = 0; un < 16; ++un) {
;         const int ps = un >> 1, hf = un & 1;
;         const int ai = ps >> 2, m = ps & 3;
;         char* reg = smem + ((ps & 1) ? 6 * HT_B : 2 * HT_B);
;         if (hf == 0) {
; #pragma unroll
;           for (int bj = 0; bj < 2; ++bj)
; #pragma unroll
;             for (int n = 0; n < 2; ++n) {
;               const int c4 = bj * 32 + wc * 8 + n * 4 + fq;
;               *(f32x4*)(reg + lwr + ((c4 ^ fr) << 4)) = acc[ai][bj][m][n];
;             }
;           WAIT_L(0);
;           BAR();
;         }
;         if (un + 1 < 16) {
;           const int ps2 = (un + 1) >> 1, hf2 = (un + 1) & 1;
;           const int off2 = ((ps2 >> 2) * 128 + (ps2 & 3) * 16 + 2 * hf2) * 1024;
;           xv[(un + 1) & 1][0] = *(const float4*)(xinb + off2);
;           xv[(un + 1) & 1][1] = *(const float4*)(xinb + off2 + 1024);
;         }
; #pragma unroll
;         for (int r = 0; r < 2; ++r) {
;           const int k = 2 * hf + r;
;           const int roff = ai * 128 + m * 16 + k;
;           const f32x4 av = *(const f32x4*)(reg + ((lrd + k * 1024) ^ (k << 4)));
;           float4 v = xv[un & 1][r];
;           v.x += av[0]; v.y += av[1]; v.z += av[2]; v.w += av[3];
;           *(float4*)(xoutb + (long)roff * 1024) = v;
;           if (xbb) {
;             uint2 pk;
;             pk.x = pack2(v.x, v.y);
;             pk.y = pack2(v.z, v.w);
;             *(uint2*)(xbb + (long)roff * 1024) = pk;
;           }
;           if (ssnb) {
;             float part = (v.x * v.x + v.y * v.y) + (v.z * v.z + v.w * v.w);
; #pragma unroll
;             for (int o = 32; o >= 1; o >>= 1) part += __shfl_xor(part, o);
;             if (ln == 0) ssnb[roff * 4] = part;
;           }
;         }
;       }
.LBB0_444:
.LBB0_445:
	ds_write_b128 v100, v[16:19] offset:32768
	ds_write_b128 v101, v[20:23] offset:32768
	ds_write_b128 v102, v[24:27] offset:32768
	ds_write_b128 v103, v[28:31] offset:32768
	v_add_co_u32_e32 v16, vcc, 0xa2000, v136
	s_waitcnt lgkmcnt(0)
	s_barrier
	s_nop 0
	v_addc_co_u32_e32 v17, vcc, 0, v137, vcc
	v_add_co_u32_e32 v18, vcc, 0xa3000, v136
	s_nop 1
	v_addc_co_u32_e32 v19, vcc, 0, v137, vcc
	global_load_dwordx4 v[28:31], v[16:17], off
	global_load_dwordx4 v[20:23], v[18:19], off
	ds_read_b128 v[16:19], v138 offset:32768
	v_add_co_u32_e32 v24, vcc, 0xa0000, v134
	s_waitcnt vmcnt(5) lgkmcnt(0)
	v_pk_add_f32 v[16:17], v[40:41], v[16:17]
	v_addc_co_u32_e32 v25, vcc, 0, v135, vcc
	v_pk_add_f32 v[18:19], v[42:43], v[18:19]
	s_and_b64 vcc, exec, s[8:9]
	global_store_dwordx4 v[24:25], v[16:19], off
	s_cbranch_vccnz .LBB0_447
	v_add_co_u32_e32 v26, vcc, 0x50000, v132
	v_cvt_pk_bf16_f32 v24, v16, v17
	v_cvt_pk_bf16_f32 v25, v18, v19
	v_addc_co_u32_e32 v27, vcc, 0, v133, vcc
	global_store_dwordx2 v[26:27], v[24:25], off
.LBB0_447:
	s_and_b64 vcc, exec, s[10:11]
	s_cbranch_vccnz .LBB0_451
	v_pk_mul_f32 v[16:17], v[16:17], v[16:17]
	v_pk_mul_f32 v[18:19], v[18:19], v[18:19]
	v_add_f32_e32 v16, v16, v17
	v_add_f32_e32 v18, v18, v19
	v_add_f32_e32 v16, v16, v18
	s_nop 1
	v_add_f32_dpp v16, v16, v16 quad_perm:[1,0,3,2] row_mask:0xf bank_mask:0xf
	s_nop 1
	v_add_f32_dpp v16, v16, v16 quad_perm:[2,3,0,1] row_mask:0xf bank_mask:0xf
	s_nop 1
	v_add_f32_dpp v16, v16, v16 row_half_mirror row_mask:0xf bank_mask:0xf
	s_nop 1
	v_add_f32_dpp v16, v16, v16 row_mirror row_mask:0xf bank_mask:0xf
	s_nop 1
	v_add_f32_dpp v16, v16, v16 row_bcast:15 row_mask:0xa bank_mask:0xf
	s_nop 1
	v_add_f32_dpp v16, v16, v16 row_bcast:31 row_mask:0xc bank_mask:0xf
	s_mov_b64 s[50:51], exec
	s_lshl_b64 exec, 1, 63
	global_store_dword v153, v16, s[56:57] offset:2560
	s_mov_b64 exec, s[50:51]
.LBB0_450:
.LBB0_451:
	s_waitcnt lgkmcnt(0)
	ds_read_b128 v[16:19], v139 offset:33792
	v_add_co_u32_e32 v24, vcc, 0xa1000, v134
	s_waitcnt vmcnt(5) lgkmcnt(0)
	v_pk_add_f32 v[16:17], v[32:33], v[16:17]
	v_addc_co_u32_e32 v25, vcc, 0, v135, vcc
	v_pk_add_f32 v[18:19], v[34:35], v[18:19]
	s_and_b64 vcc, exec, s[8:9]
	global_store_dwordx4 v[24:25], v[16:19], off
	s_cbranch_vccnz .LBB0_453
	v_add_co_u32_e32 v26, vcc, 0x50000, v132
	v_cvt_pk_bf16_f32 v24, v16, v17
	v_cvt_pk_bf16_f32 v25, v18, v19
	v_addc_co_u32_e32 v27, vcc, 0, v133, vcc
	global_store_dwordx2 v[26:27], v[24:25], off offset:2048
.LBB0_453:
	s_and_b64 vcc, exec, s[10:11]
	s_cbranch_vccnz .LBB0_457
	v_pk_mul_f32 v[16:17], v[16:17], v[16:17]
	v_pk_mul_f32 v[18:19], v[18:19], v[18:19]
	v_add_f32_e32 v16, v16, v17
	v_add_f32_e32 v18, v18, v19
	v_add_f32_e32 v16, v16, v18
	s_nop 1
	v_add_f32_dpp v16, v16, v16 quad_perm:[1,0,3,2] row_mask:0xf bank_mask:0xf
	s_nop 1
	v_add_f32_dpp v16, v16, v16 quad_perm:[2,3,0,1] row_mask:0xf bank_mask:0xf
	s_nop 1
	v_add_f32_dpp v16, v16, v16 row_half_mirror row_mask:0xf bank_mask:0xf
	s_nop 1
	v_add_f32_dpp v16, v16, v16 row_mirror row_mask:0xf bank_mask:0xf
	s_nop 1
	v_add_f32_dpp v16, v16, v16 row_bcast:15 row_mask:0xa bank_mask:0xf
	s_nop 1
	v_add_f32_dpp v16, v16, v16 row_bcast:31 row_mask:0xc bank_mask:0xf
	s_mov_b64 s[50:51], exec
	s_lshl_b64 exec, 1, 63
	global_store_dword v153, v16, s[56:57] offset:2576
	s_mov_b64 exec, s[50:51]
.LBB0_456:
.LBB0_457:
	v_add_co_u32_e32 v16, vcc, 0xb0000, v136
	s_waitcnt lgkmcnt(0)
	s_nop 0
	v_addc_co_u32_e32 v17, vcc, 0, v137, vcc
	v_add_co_u32_e32 v18, vcc, 0xb1000, v136
	s_nop 1
	v_addc_co_u32_e32 v19, vcc, 0, v137, vcc
	global_load_dwordx4 v[24:27], v[16:17], off
	s_nop 0
	global_load_dwordx4 v[16:19], v[18:19], off
	ds_read_b128 v[32:35], v128 offset:34816
	s_waitcnt vmcnt(5) lgkmcnt(0)
	v_pk_add_f32 v[28:29], v[28:29], v[32:33]
	v_add_co_u32_e32 v32, vcc, 0xa2000, v134
	v_pk_add_f32 v[30:31], v[30:31], v[34:35]
	s_nop 0
	v_addc_co_u32_e32 v33, vcc, 0, v135, vcc
	s_and_b64 vcc, exec, s[8:9]
	global_store_dwordx4 v[32:33], v[28:31], off
	s_cbranch_vccnz .LBB0_459
	v_add_co_u32_e32 v34, vcc, 0x51000, v132
	v_cvt_pk_bf16_f32 v32, v28, v29
	v_cvt_pk_bf16_f32 v33, v30, v31
	v_addc_co_u32_e32 v35, vcc, 0, v133, vcc
	global_store_dwordx2 v[34:35], v[32:33], off
.LBB0_459:
	s_and_b64 vcc, exec, s[10:11]
	s_cbranch_vccnz .LBB0_463
	v_pk_mul_f32 v[28:29], v[28:29], v[28:29]
	v_pk_mul_f32 v[30:31], v[30:31], v[30:31]
	v_add_f32_e32 v28, v28, v29
	v_add_f32_e32 v30, v30, v31
	v_add_f32_e32 v28, v28, v30
	s_nop 1
	v_add_f32_dpp v28, v28, v28 quad_perm:[1,0,3,2] row_mask:0xf bank_mask:0xf
	s_nop 1
	v_add_f32_dpp v28, v28, v28 quad_perm:[2,3,0,1] row_mask:0xf bank_mask:0xf
	s_nop 1
	v_add_f32_dpp v28, v28, v28 row_half_mirror row_mask:0xf bank_mask:0xf
	s_nop 1
	v_add_f32_dpp v28, v28, v28 row_mirror row_mask:0xf bank_mask:0xf
	s_nop 1
	v_add_f32_dpp v28, v28, v28 row_bcast:15 row_mask:0xa bank_mask:0xf
	s_nop 1
	v_add_f32_dpp v28, v28, v28 row_bcast:31 row_mask:0xc bank_mask:0xf
	s_mov_b64 s[50:51], exec
	s_lshl_b64 exec, 1, 63
	global_store_dword v153, v28, s[56:57] offset:2592
	s_mov_b64 exec, s[50:51]
.LBB0_462:
.LBB0_463:
	s_waitcnt lgkmcnt(0)
	ds_read_b128 v[28:31], v120 offset:35840
	s_waitcnt vmcnt(5) lgkmcnt(0)
	v_pk_add_f32 v[20:21], v[20:21], v[28:29]
	v_add_co_u32_e32 v28, vcc, 0xa3000, v134
	v_pk_add_f32 v[22:23], v[22:23], v[30:31]
	s_nop 0
	v_addc_co_u32_e32 v29, vcc, 0, v135, vcc
	s_and_b64 vcc, exec, s[8:9]
	global_store_dwordx4 v[28:29], v[20:23], off
	s_cbranch_vccnz .LBB0_465
	v_add_co_u32_e32 v30, vcc, 0x51000, v132
	v_cvt_pk_bf16_f32 v28, v20, v21
	v_cvt_pk_bf16_f32 v29, v22, v23
	v_addc_co_u32_e32 v31, vcc, 0, v133, vcc
	global_store_dwordx2 v[30:31], v[28:29], off offset:2048
;   __device__ __forceinline__ bf16* z() const { return (bf16*)(ws + OFF_z); }
; #define BAR() __builtin_amdgcn_s_barrier()
; #define WAIT_L(n) asm volatile("s_waitcnt lgkmcnt(" #n ")" ::: "memory")
; __device__ __forceinline__ void gemm_phase(const GemmArgs& a, char* smem) {
;     ...
;       float4 xv[2][2];
;       xv[0][0] = *(const float4*)(xinb);
;       xv[0][1] = *(const float4*)(xinb + 1024);
; #pragma unroll
;       for (int un = 0; un < 16; ++un) {
;         const int ps = un >> 1, hf = un & 1;
;         const int ai = ps >> 2, m = ps & 3;
;         char* reg = smem + ((ps & 1) ? 6 * HT_B : 2 * HT_B);
;         if (hf == 0) {
; #pragma unroll
;           for (int bj = 0; bj < 2; ++bj)
; #pragma unroll
;             for (int n = 0; n < 2; ++n) {
;               const int c4 = bj * 32 + wc * 8 + n * 4 + fq;
;               *(f32x4*)(reg + lwr + ((c4 ^ fr) << 4)) = acc[ai][bj][m][n];
;             }
;           WAIT_L(0);
;           BAR();
;         }
;         if (un + 1 < 16) {
;           const int ps2 = (un + 1) >> 1, hf2 = (un + 1) & 1;
;           const int off2 = ((ps2 >> 2) * 128 + (ps2 & 3) * 16 + 2 * hf2) * 1024;
;           xv[(un + 1) & 1][0] = *(const float4*)(xinb + off2);
;           xv[(un + 1) & 1][1] = *(const float4*)(xinb + off2 + 1024);
;         }
; #pragma unroll
;         for (int r = 0; r < 2; ++r) {
;           const int k = 2 * hf + r;
;           const int roff = ai * 128 + m * 16 + k;
;           const f32x4 av = *(const f32x4*)(reg + ((lrd + k * 1024) ^ (k << 4)));
;           float4 v = xv[un & 1][r];
;           v.x += av[0]; v.y += av[1]; v.z += av[2]; v.w += av[3];
;           *(float4*)(xoutb + (long)roff * 1024) = v;
;           if (xbb) {
;             uint2 pk;
;             pk.x = pack2(v.x, v.y);
;             pk.y = pack2(v.z, v.w);
;             *(uint2*)(xbb + (long)roff * 1024) = pk;
;           }
;           if (ssnb) {
;             float part = (v.x * v.x + v.y * v.y) + (v.z * v.z + v.w * v.w);
; #pragma unroll
;             for (int o = 32; o >= 1; o >>= 1) part += __shfl_xor(part, o);
;             if (ln == 0) ssnb[roff * 4] = part;
;           }
;         }
;       }
.LBB0_465:
	s_and_b64 vcc, exec, s[10:11]
	s_cbranch_vccnz .LBB0_469
	v_pk_mul_f32 v[20:21], v[20:21], v[20:21]
	v_pk_mul_f32 v[22:23], v[22:23], v[22:23]
	v_add_f32_e32 v20, v20, v21
	v_add_f32_e32 v22, v22, v23
	v_add_f32_e32 v20, v20, v22
	s_nop 1
	v_add_f32_dpp v20, v20, v20 quad_perm:[1,0,3,2] row_mask:0xf bank_mask:0xf
	s_nop 1
	v_add_f32_dpp v20, v20, v20 quad_perm:[2,3,0,1] row_mask:0xf bank_mask:0xf
	s_nop 1
	v_add_f32_dpp v20, v20, v20 row_half_mirror row_mask:0xf bank_mask:0xf
	s_nop 1
	v_add_f32_dpp v20, v20, v20 row_mirror row_mask:0xf bank_mask:0xf
	s_nop 1
	v_add_f32_dpp v20, v20, v20 row_bcast:15 row_mask:0xa bank_mask:0xf
	s_nop 1
	v_add_f32_dpp v20, v20, v20 row_bcast:31 row_mask:0xc bank_mask:0xf
	s_mov_b64 s[50:51], exec
	s_lshl_b64 exec, 1, 63
	global_store_dword v153, v20, s[56:57] offset:2608
	s_mov_b64 exec, s[50:51]
.LBB0_468:
.LBB0_469:
	ds_write_b128 v112, v[0:3]
	ds_write_b128 v113, v[4:7]
	ds_write_b128 v114, v[8:11]
	ds_write_b128 v115, v[12:15]
	v_add_co_u32_e32 v0, vcc, 0xb2000, v136
	s_waitcnt lgkmcnt(0)
	s_barrier
	s_nop 0
	v_addc_co_u32_e32 v1, vcc, 0, v137, vcc
	v_add_co_u32_e32 v2, vcc, 0xb3000, v136
	s_nop 1
	v_addc_co_u32_e32 v3, vcc, 0, v137, vcc
	global_load_dwordx4 v[4:7], v[0:1], off
	s_nop 0
	global_load_dwordx4 v[0:3], v[2:3], off
	ds_read_b128 v[8:11], v121
	v_add_co_u32_e32 v12, vcc, 0xb0000, v134
	s_waitcnt vmcnt(5) lgkmcnt(0)
	v_pk_add_f32 v[8:9], v[24:25], v[8:9]
	v_addc_co_u32_e32 v13, vcc, 0, v135, vcc
	v_pk_add_f32 v[10:11], v[26:27], v[10:11]
	s_and_b64 vcc, exec, s[8:9]
	global_store_dwordx4 v[12:13], v[8:11], off
	s_cbranch_vccnz .LBB0_471
	v_add_co_u32_e32 v14, vcc, 0x58000, v132
	v_cvt_pk_bf16_f32 v12, v8, v9
	v_cvt_pk_bf16_f32 v13, v10, v11
	v_addc_co_u32_e32 v15, vcc, 0, v133, vcc
	global_store_dwordx2 v[14:15], v[12:13], off
.LBB0_471:
	s_and_b64 vcc, exec, s[10:11]
	s_cbranch_vccnz .LBB0_475
	v_pk_mul_f32 v[8:9], v[8:9], v[8:9]
	v_pk_mul_f32 v[10:11], v[10:11], v[10:11]
	v_add_f32_e32 v8, v8, v9
	v_add_f32_e32 v10, v10, v11
	v_add_f32_e32 v8, v8, v10
	s_nop 1
	v_add_f32_dpp v8, v8, v8 quad_perm:[1,0,3,2] row_mask:0xf bank_mask:0xf
	s_nop 1
	v_add_f32_dpp v8, v8, v8 quad_perm:[2,3,0,1] row_mask:0xf bank_mask:0xf
	s_nop 1
	v_add_f32_dpp v8, v8, v8 row_half_mirror row_mask:0xf bank_mask:0xf
	s_nop 1
	v_add_f32_dpp v8, v8, v8 row_mirror row_mask:0xf bank_mask:0xf
	s_nop 1
	v_add_f32_dpp v8, v8, v8 row_bcast:15 row_mask:0xa bank_mask:0xf
	s_nop 1
	v_add_f32_dpp v8, v8, v8 row_bcast:31 row_mask:0xc bank_mask:0xf
	s_mov_b64 s[50:51], exec
	s_lshl_b64 exec, 1, 63
	global_store_dword v153, v8, s[56:57] offset:2816
	s_mov_b64 exec, s[50:51]
.LBB0_474:
.LBB0_475:
	s_waitcnt lgkmcnt(0)
	ds_read_b128 v[8:11], v122
	v_add_co_u32_e32 v12, vcc, 0xb1000, v134
	s_waitcnt vmcnt(5) lgkmcnt(0)
	v_pk_add_f32 v[8:9], v[16:17], v[8:9]
	v_addc_co_u32_e32 v13, vcc, 0, v135, vcc
	v_pk_add_f32 v[10:11], v[18:19], v[10:11]
	s_and_b64 vcc, exec, s[8:9]
	global_store_dwordx4 v[12:13], v[8:11], off
	s_cbranch_vccnz .LBB0_477
	v_add_co_u32_e32 v14, vcc, 0x58000, v132
	v_cvt_pk_bf16_f32 v12, v8, v9
	v_cvt_pk_bf16_f32 v13, v10, v11
	v_addc_co_u32_e32 v15, vcc, 0, v133, vcc
	global_store_dwordx2 v[14:15], v[12:13], off offset:2048
.LBB0_477:
	s_and_b64 vcc, exec, s[10:11]
	s_cbranch_vccnz .LBB0_481
	v_pk_mul_f32 v[8:9], v[8:9], v[8:9]
	v_pk_mul_f32 v[10:11], v[10:11], v[10:11]
	v_add_f32_e32 v8, v8, v9
	v_add_f32_e32 v10, v10, v11
	v_add_f32_e32 v8, v8, v10
	s_nop 1
	v_add_f32_dpp v8, v8, v8 quad_perm:[1,0,3,2] row_mask:0xf bank_mask:0xf
	s_nop 1
	v_add_f32_dpp v8, v8, v8 quad_perm:[2,3,0,1] row_mask:0xf bank_mask:0xf
	s_nop 1
	v_add_f32_dpp v8, v8, v8 row_half_mirror row_mask:0xf bank_mask:0xf
	s_nop 1
	v_add_f32_dpp v8, v8, v8 row_mirror row_mask:0xf bank_mask:0xf
	s_nop 1
	v_add_f32_dpp v8, v8, v8 row_bcast:15 row_mask:0xa bank_mask:0xf
	s_nop 1
	v_add_f32_dpp v8, v8, v8 row_bcast:31 row_mask:0xc bank_mask:0xf
	s_mov_b64 s[50:51], exec
	s_lshl_b64 exec, 1, 63
	global_store_dword v153, v8, s[56:57] offset:2832
	s_mov_b64 exec, s[50:51]
.LBB0_480:
.LBB0_481:
	s_waitcnt lgkmcnt(0)
	ds_read_b128 v[8:11], v116
	s_waitcnt vmcnt(3) lgkmcnt(0)
	v_pk_add_f32 v[4:5], v[4:5], v[8:9]
	v_add_co_u32_e32 v8, vcc, 0xb2000, v134
	v_pk_add_f32 v[6:7], v[6:7], v[10:11]
	s_nop 0
	v_addc_co_u32_e32 v9, vcc, 0, v135, vcc
	s_and_b64 vcc, exec, s[8:9]
	global_store_dwordx4 v[8:9], v[4:7], off
	s_cbranch_vccnz .LBB0_483
	v_add_co_u32_e32 v10, vcc, 0x59000, v132
	v_cvt_pk_bf16_f32 v8, v4, v5
	v_cvt_pk_bf16_f32 v9, v6, v7
	v_addc_co_u32_e32 v11, vcc, 0, v133, vcc
	global_store_dwordx2 v[10:11], v[8:9], off
.LBB0_483:
	s_and_b64 vcc, exec, s[10:11]
	s_cbranch_vccnz .LBB0_487
	v_pk_mul_f32 v[4:5], v[4:5], v[4:5]
	v_pk_mul_f32 v[6:7], v[6:7], v[6:7]
	v_add_f32_e32 v4, v4, v5
	v_add_f32_e32 v6, v6, v7
	v_add_f32_e32 v4, v4, v6
	s_nop 1
	v_add_f32_dpp v4, v4, v4 quad_perm:[1,0,3,2] row_mask:0xf bank_mask:0xf
	s_nop 1
	v_add_f32_dpp v4, v4, v4 quad_perm:[2,3,0,1] row_mask:0xf bank_mask:0xf
	s_nop 1
	v_add_f32_dpp v4, v4, v4 row_half_mirror row_mask:0xf bank_mask:0xf
	s_nop 1
	v_add_f32_dpp v4, v4, v4 row_mirror row_mask:0xf bank_mask:0xf
	s_nop 1
	v_add_f32_dpp v4, v4, v4 row_bcast:15 row_mask:0xa bank_mask:0xf
	s_nop 1
	v_add_f32_dpp v4, v4, v4 row_bcast:31 row_mask:0xc bank_mask:0xf
	s_mov_b64 s[50:51], exec
	s_lshl_b64 exec, 1, 63
	global_store_dword v153, v4, s[56:57] offset:2848
	s_mov_b64 exec, s[50:51]
.LBB0_486:
.LBB0_487:
	s_waitcnt lgkmcnt(0)
	ds_read_b128 v[4:7], v108
	s_waitcnt vmcnt(3) lgkmcnt(0)
	v_pk_add_f32 v[0:1], v[0:1], v[4:5]
	v_add_co_u32_e32 v4, vcc, 0xb3000, v134
	v_pk_add_f32 v[2:3], v[2:3], v[6:7]
	s_nop 0
	v_addc_co_u32_e32 v5, vcc, 0, v135, vcc
	s_and_b64 vcc, exec, s[8:9]
	global_store_dwordx4 v[4:5], v[0:3], off
	s_cbranch_vccnz .LBB0_489
	v_add_co_u32_e32 v6, vcc, 0x59000, v132
	v_cvt_pk_bf16_f32 v4, v0, v1
	v_cvt_pk_bf16_f32 v5, v2, v3
	v_addc_co_u32_e32 v7, vcc, 0, v133, vcc
	global_store_dwordx2 v[6:7], v[4:5], off offset:2048
.LBB0_489:
	s_and_b64 vcc, exec, s[10:11]
	s_cbranch_vccnz .LBB0_190
	v_pk_mul_f32 v[0:1], v[0:1], v[0:1]
	v_pk_mul_f32 v[2:3], v[2:3], v[2:3]
	v_add_f32_e32 v0, v0, v1
	v_add_f32_e32 v2, v2, v3
	v_add_f32_e32 v0, v0, v2
	s_nop 1
	v_add_f32_dpp v0, v0, v0 quad_perm:[1,0,3,2] row_mask:0xf bank_mask:0xf
	s_nop 1
	v_add_f32_dpp v0, v0, v0 quad_perm:[2,3,0,1] row_mask:0xf bank_mask:0xf
	s_nop 1
	v_add_f32_dpp v0, v0, v0 row_half_mirror row_mask:0xf bank_mask:0xf
	s_nop 1
	v_add_f32_dpp v0, v0, v0 row_mirror row_mask:0xf bank_mask:0xf
	s_nop 1
	v_add_f32_dpp v0, v0, v0 row_bcast:15 row_mask:0xa bank_mask:0xf
	s_nop 1
	v_add_f32_dpp v0, v0, v0 row_bcast:31 row_mask:0xc bank_mask:0xf
	s_mov_b64 s[8:9], exec
	s_lshl_b64 exec, 1, 63
	global_store_dword v153, v0, s[56:57] offset:2864
	s_mov_b64 exec, s[8:9]
	s_branch .LBB0_189
